# sc1 write-through stores in P4/P5, L2 writeback removed at seams 4,5
# speedup vs baseline: 1.0076x; 1.0076x over previous
.LBB0_351:
	v_add_u32_e32 v10, s15, v171
	v_add_u32_e32 v34, 16, v10
	v_add_u32_e32 v38, 32, v10
	v_ashrrev_i32_e32 v11, 31, v10
	v_ashrrev_i32_e32 v35, 31, v34
	v_ashrrev_i32_e32 v39, 31, v38
	v_lshlrev_b64 v[50:51], 11, v[10:11]
	v_lshlrev_b64 v[54:55], 11, v[34:35]
	v_lshlrev_b64 v[58:59], 11, v[38:39]
	v_lshl_add_u64 v[30:31], v[4:5], 0, v[50:51]
	v_lshl_add_u64 v[34:35], v[4:5], 0, v[54:55]
	v_lshl_add_u64 v[38:39], v[4:5], 0, v[58:59]
	global_load_dwordx4 v[26:29], v[2:3], off
	v_add_u32_e32 v10, 48, v10
	global_load_dwordx4 v[30:33], v[30:31], off
	v_ashrrev_i32_e32 v11, 31, v10
	global_load_dwordx4 v[34:37], v[34:35], off
	v_lshlrev_b64 v[10:11], 11, v[10:11]
	global_load_dwordx4 v[38:41], v[38:39], off
	v_lshl_add_u64 v[42:43], v[4:5], 0, v[10:11]
	global_load_dwordx4 v[42:45], v[42:43], off
	s_nop 0
	global_load_dwordx4 v[46:49], v[2:3], off offset:64
	v_lshl_add_u64 v[66:67], s[36:37], 0, v[50:51]
	v_lshl_add_u64 v[68:69], s[36:37], 0, v[54:55]
	v_lshl_add_u64 v[50:51], v[66:67], 0, v[0:1]
	v_lshl_add_u64 v[54:55], v[68:69], 0, v[0:1]
	v_lshl_add_u64 v[70:71], s[36:37], 0, v[58:59]
	global_load_dwordx4 v[50:53], v[50:51], off
	v_lshl_add_u64 v[58:59], v[70:71], 0, v[0:1]
	global_load_dwordx4 v[54:57], v[54:55], off
	v_lshl_add_u64 v[10:11], s[36:37], 0, v[10:11]
	global_load_dwordx4 v[58:61], v[58:59], off
	v_lshl_add_u64 v[62:63], v[10:11], 0, v[0:1]
	v_lshl_add_u64 v[72:73], v[68:69], 0, v[6:7]
	s_waitcnt vmcnt(7)
	v_mfma_f32_16x16x32_bf16 v[30:33], v[30:33], v[26:29], 0
	s_waitcnt vmcnt(6)
	v_mfma_f32_16x16x32_bf16 v[34:37], v[34:37], v[26:29], 0
	s_waitcnt vmcnt(5)
	v_mfma_f32_16x16x32_bf16 v[38:41], v[38:41], v[26:29], 0
	s_waitcnt vmcnt(4)
	v_mfma_f32_16x16x32_bf16 v[26:29], v[42:45], v[26:29], 0
	global_load_dwordx4 v[42:45], v[62:63], off
	v_lshl_add_u64 v[62:63], v[66:67], 0, v[6:7]
	v_lshl_add_u64 v[66:67], v[66:67], 0, v[8:9]
	s_waitcnt vmcnt(3)
	v_mfma_f32_16x16x32_bf16 v[30:33], v[50:53], v[46:49], v[30:33]
	global_load_dwordx4 v[50:53], v[62:63], off
	s_nop 0
	global_load_dwordx4 v[62:65], v[2:3], off offset:128
	s_waitcnt vmcnt(4)
	v_mfma_f32_16x16x32_bf16 v[34:37], v[54:57], v[46:49], v[34:37]
	global_load_dwordx4 v[54:57], v[72:73], off
	v_lshl_add_u64 v[72:73], v[70:71], 0, v[6:7]
	s_waitcnt vmcnt(4)
	v_mfma_f32_16x16x32_bf16 v[38:41], v[58:61], v[46:49], v[38:41]
	global_load_dwordx4 v[58:61], v[72:73], off
	v_lshl_add_u64 v[72:73], v[10:11], 0, v[6:7]
	v_lshl_add_u64 v[10:11], v[10:11], 0, v[8:9]
	s_waitcnt vmcnt(2)
	v_mfma_f32_16x16x32_bf16 v[30:33], v[50:53], v[62:65], v[30:33]
	v_mfma_f32_16x16x32_bf16 v[26:29], v[42:45], v[46:49], v[26:29]
	global_load_dwordx4 v[42:45], v[72:73], off
	global_load_dwordx4 v[46:49], v[2:3], off offset:192
	global_load_dwordx4 v[50:53], v[66:67], off
	s_waitcnt vmcnt(4)
	v_mfma_f32_16x16x32_bf16 v[34:37], v[54:57], v[62:65], v[34:37]
	s_waitcnt vmcnt(3)
	v_mfma_f32_16x16x32_bf16 v[38:41], v[58:61], v[62:65], v[38:41]
	s_waitcnt vmcnt(2)
	v_mfma_f32_16x16x32_bf16 v[26:29], v[42:45], v[62:65], v[26:29]
	global_load_dwordx4 v[42:45], v[10:11], off
	v_lshl_add_u64 v[66:67], v[68:69], 0, v[8:9]
	global_load_dwordx4 v[54:57], v[66:67], off
	v_lshl_add_u64 v[66:67], v[70:71], 0, v[8:9]
	global_load_dwordx4 v[58:61], v[66:67], off
	v_add_u32_e32 v10, s15, v204
	v_ashrrev_i32_e32 v11, 31, v10
	s_waitcnt vmcnt(3)
	v_mfma_f32_16x16x32_bf16 v[30:33], v[50:53], v[46:49], v[30:33]
	v_lshlrev_b64 v[50:51], 6, v[10:11]
	v_lshl_add_u64 v[66:67], s[60:61], 0, v[50:51]
	global_load_dwordx4 v[50:53], v[66:67], off
	v_lshl_add_u64 v[10:11], v[10:11], 2, s[38:39]
	s_waitcnt vmcnt(3)
	v_mfma_f32_16x16x32_bf16 v[26:29], v[42:45], v[46:49], v[26:29]
	s_waitcnt vmcnt(0)
	v_add_f32_e32 v25, v50, v51
	v_mfma_f32_16x16x32_bf16 v[34:37], v[54:57], v[46:49], v[34:37]
	global_load_dwordx4 v[54:57], v[66:67], off offset:16
	global_load_dwordx4 v[62:65], v[66:67], off offset:32
	v_mfma_f32_16x16x32_bf16 v[38:41], v[58:61], v[46:49], v[38:41]
	global_load_dwordx4 v[58:61], v[66:67], off offset:48
	ds_write2_b32 v19, v30, v31 offset1:16
	ds_write2_b32 v19, v32, v33 offset0:32 offset1:48
	s_nop 1
	ds_write2_b32 v22, v34, v35 offset1:16
	ds_write2_b32 v22, v36, v37 offset0:32 offset1:48
	s_nop 0
	ds_write2_b32 v23, v38, v39 offset1:16
	ds_write2_b32 v23, v40, v41 offset0:32 offset1:48
	ds_write2_b32 v24, v26, v27 offset1:16
	ds_write2_b32 v24, v28, v29 offset0:32 offset1:48
	s_waitcnt lgkmcnt(0)
	s_barrier
	global_load_dword v34, v1, s[42:43]
	v_add_f32_e32 v26, v52, v53
	v_add_f32_e32 v25, v25, v26
	s_waitcnt vmcnt(3)
	v_add_f32_e32 v27, v54, v55
	v_add_f32_e32 v28, v56, v57
	s_waitcnt vmcnt(2)
	v_add_f32_e32 v29, v62, v63
	v_add_f32_e32 v30, v64, v65
	v_add_f32_e32 v26, v27, v28
	s_waitcnt vmcnt(1)
	v_add_f32_e32 v31, v58, v59
	v_add_f32_e32 v32, v60, v61
	v_add_f32_e32 v27, v29, v30
	v_add_f32_e32 v25, v25, v26
	v_add_f32_e32 v28, v31, v32
	v_add_f32_e32 v25, v25, v27
	v_add_f32_e32 v25, v25, v28
	v_fmamk_f32 v25, v25, 0x3a800000, v20
	v_mul_f32_e32 v26, 0x4f800000, v25
	v_cmp_gt_f32_e32 vcc, s57, v25
	s_nop 1
	v_cndmask_b32_e32 v25, v25, v26, vcc
	v_sqrt_f32_e32 v26, v25
	s_nop 0
	v_add_u32_e32 v27, -1, v26
	v_add_u32_e32 v28, 1, v26
	v_fma_f32 v29, -v27, v26, v25
	v_fma_f32 v30, -v28, v26, v25
	v_cmp_ge_f32_e64 s[22:23], 0, v29
	s_nop 1
	v_cndmask_b32_e64 v26, v26, v27, s[22:23]
	v_cmp_lt_f32_e64 s[22:23], 0, v30
	s_nop 1
	v_cndmask_b32_e64 v26, v26, v28, s[22:23]
	v_mul_f32_e32 v27, 0x37800000, v26
	v_cndmask_b32_e32 v26, v26, v27, vcc
	v_cmp_class_f32_e32 vcc, v25, v21
	s_nop 1
	v_cndmask_b32_e32 v25, v26, v25, vcc
	v_div_scale_f32 v35, s[22:23], v25, v25, 1.0
	v_rcp_f32_e32 v37, v35
	ds_read2st64_b32 v[26:27], v12 offset1:16
	ds_read2st64_b32 v[28:29], v12 offset0:32 offset1:48
	ds_read2st64_b32 v[30:31], v12 offset0:64 offset1:80
	ds_read2st64_b32 v[32:33], v12 offset0:96 offset1:112
	v_div_scale_f32 v36, vcc, 1.0, v25, 1.0
	v_fma_f32 v38, -v35, v37, 1.0
	s_waitcnt lgkmcnt(3)
	v_add_f32_e32 v26, 0, v26
	v_fmac_f32_e32 v37, v38, v37
	v_add_f32_e32 v26, v26, v27
	v_mul_f32_e32 v38, v36, v37
	s_waitcnt lgkmcnt(2)
	v_add_f32_e32 v26, v26, v28
	v_fma_f32 v39, -v35, v38, v36
	v_add_f32_e32 v26, v26, v29
	v_fmac_f32_e32 v38, v39, v37
	s_waitcnt lgkmcnt(1)
	v_add_f32_e32 v26, v26, v30
	v_fma_f32 v27, -v35, v38, v36
	v_add_f32_e32 v26, v26, v31
	v_div_fmas_f32 v27, v27, v37, v38
	s_waitcnt lgkmcnt(0)
	v_add_f32_e32 v26, v26, v32
	v_div_fixup_f32 v25, v27, v25, 1.0
	v_add_f32_e32 v26, v26, v33
	s_waitcnt vmcnt(0)
	v_fmac_f32_e32 v34, v25, v26
	v_mul_f32_e64 v26, |v34|, s64
	v_exp_f32_e32 v26, v26
	v_min_f32_e32 v27, 0, v34
	v_lshl_add_u64 v[28:29], v[10:11], 0, s[46:47]
	v_add_f32_e32 v26, 1.0, v26
	v_log_f32_e32 v26, v26
	s_nop 0
	v_fmac_f32_e32 v27, 0xbf317218, v26
	ds_bpermute_b32 v26, v13, v27
	s_waitcnt lgkmcnt(0)
	v_add_f32_e32 v26, v27, v26
	v_cndmask_b32_e64 v26, v26, v27, s[8:9]
	ds_bpermute_b32 v27, v14, v26
	s_waitcnt lgkmcnt(0)
	v_add_f32_e32 v27, v26, v27
	v_cndmask_b32_e64 v26, v27, v26, s[10:11]
	ds_bpermute_b32 v27, v15, v26
	s_waitcnt lgkmcnt(0)
	v_add_f32_e32 v27, v26, v27
	v_cndmask_b32_e64 v26, v27, v26, s[12:13]
	ds_bpermute_b32 v27, v16, v26
	s_waitcnt lgkmcnt(0)
	v_add_f32_e32 v27, v26, v27
	v_cndmask_b32_e64 v26, v27, v26, s[16:17]
	ds_bpermute_b32 v27, v17, v26
	s_waitcnt lgkmcnt(0)
	v_add_f32_e32 v27, v26, v27
	v_cndmask_b32_e64 v27, v27, v26, s[18:19]
	ds_bpermute_b32 v26, v18, v27
	s_waitcnt lgkmcnt(0)
	v_add_f32_e32 v26, v27, v26
	v_cndmask_b32_e64 v27, v26, v27, s[20:21]
	global_store_dword v[28:29], v27, off sc1
	s_and_saveexec_b64 s[22:23], s[0:1]
	s_cbranch_execz .LBB0_353
	s_add_i32 s44, s14, s65
	s_ashr_i32 s45, s44, 31
	s_lshl_b64 s[44:45], s[44:45], 2
	s_add_u32 s44, s74, s44
	s_addc_u32 s45, s75, s45
	global_store_dword v1, v26, s[44:45] sc1
.LBB0_353:
	s_or_b64 exec, exec, s[22:23]
	global_load_dword v34, v1, s[42:43] offset:4
	v_add_u32_e32 v32, 4, v12
	ds_read2st64_b32 v[26:27], v32 offset1:16
	ds_read2st64_b32 v[28:29], v32 offset0:32 offset1:48
	ds_read2st64_b32 v[30:31], v32 offset0:64 offset1:80
	ds_read2st64_b32 v[32:33], v32 offset0:96 offset1:112
	v_lshl_add_u64 v[10:11], v[10:11], 0, s[48:49]
	s_waitcnt lgkmcnt(3)
	v_add_f32_e32 v26, 0, v26
	v_add_f32_e32 v26, v26, v27
	s_waitcnt lgkmcnt(2)
	v_add_f32_e32 v26, v26, v28
	v_add_f32_e32 v26, v26, v29
	s_waitcnt lgkmcnt(1)
	v_add_f32_e32 v26, v26, v30
	v_add_f32_e32 v26, v26, v31
	s_waitcnt lgkmcnt(0)
	v_add_f32_e32 v26, v26, v32
	v_add_f32_e32 v26, v26, v33
	s_waitcnt vmcnt(0)
	v_fmac_f32_e32 v34, v25, v26
	v_mul_f32_e64 v25, |v34|, s64
	v_exp_f32_e32 v25, v25
	v_min_f32_e32 v26, 0, v34
	v_add_f32_e32 v25, 1.0, v25
	v_log_f32_e32 v25, v25
	s_nop 0
	v_fmac_f32_e32 v26, 0xbf317218, v25
	ds_bpermute_b32 v25, v13, v26
	s_waitcnt lgkmcnt(0)
	v_add_f32_e32 v25, v26, v25
	v_cndmask_b32_e64 v25, v25, v26, s[8:9]
	ds_bpermute_b32 v26, v14, v25
	s_waitcnt lgkmcnt(0)
	v_add_f32_e32 v26, v25, v26
	v_cndmask_b32_e64 v25, v26, v25, s[10:11]
	ds_bpermute_b32 v26, v15, v25
	s_waitcnt lgkmcnt(0)
	v_add_f32_e32 v26, v25, v26
	v_cndmask_b32_e64 v25, v26, v25, s[12:13]
	ds_bpermute_b32 v26, v16, v25
	s_waitcnt lgkmcnt(0)
	v_add_f32_e32 v26, v25, v26
	v_cndmask_b32_e64 v25, v26, v25, s[16:17]
	ds_bpermute_b32 v26, v17, v25
	s_waitcnt lgkmcnt(0)
	v_add_f32_e32 v26, v25, v26
	v_cndmask_b32_e64 v26, v26, v25, s[18:19]
	ds_bpermute_b32 v25, v18, v26
	s_waitcnt lgkmcnt(0)
	v_add_f32_e32 v25, v26, v25
	v_cndmask_b32_e64 v26, v25, v26, s[20:21]
	global_store_dword v[10:11], v26, off sc1
	s_and_saveexec_b64 s[22:23], s[0:1]
	s_cbranch_execz .LBB0_350
	s_add_i32 s33, s14, s65
	s_add_i32 s44, s33, 0x100
	s_ashr_i32 s45, s44, 31
	s_lshl_b64 s[44:45], s[44:45], 2
	s_add_u32 s44, s74, s44
	s_addc_u32 s45, s75, s45
	global_store_dword v1, v25, s[44:45] sc1
	s_branch .LBB0_350

.LBB0_394:
	s_lshl_b32 s12, s12, 2
	s_waitcnt lgkmcnt(6)
	v_add_f32_e32 v128, v168, v186
	s_and_b32 s12, s12, 12
	v_fmamk_f32 v128, v128, 0x3a800000, v213
	s_or_b32 s12, s12, s84
	v_rsq_f32_e32 v132, v128
	v_lshlrev_b32_e32 v128, 1, v170
	v_lshl_or_b32 v168, s12, 7, v128
	v_lshl_add_u64 v[186:187], s[68:69], 0, v[168:169]
	v_lshlrev_b64 v[128:129], 11, v[200:201]
	v_lshl_add_u64 v[134:135], v[186:187], 0, v[128:129]
	v_cvt_pk_bf16_f32 v128, v144, v145
	v_cvt_pk_bf16_f32 v129, v146, v147
	v_cvt_pk_bf16_f32 v130, v148, v149
	v_cvt_pk_bf16_f32 v131, v150, v151
	global_store_dwordx4 v[134:135], v[128:131], off sc1
	v_pk_mul_f32 v[126:127], v[126:127], v[132:133] op_sel_hi:[1,0]
	v_pk_mul_f32 v[124:125], v[124:125], v[132:133] op_sel_hi:[1,0]
	v_cvt_pk_bf16_f32 v128, v152, v153
	v_cvt_pk_bf16_f32 v129, v154, v155
	v_cvt_pk_bf16_f32 v130, v156, v157
	v_cvt_pk_bf16_f32 v131, v158, v159
	global_store_dwordx4 v[134:135], v[128:131], off offset:64 sc1
	v_pk_mul_f32 v[122:123], v[122:123], v[132:133] op_sel_hi:[1,0]
	v_pk_mul_f32 v[120:121], v[120:121], v[132:133] op_sel_hi:[1,0]
	v_cndmask_b32_e64 v128, 0, 1, s[70:71]
	v_pk_mul_f32 v[118:119], v[118:119], v[132:133] op_sel_hi:[1,0]
	v_pk_mul_f32 v[116:117], v[116:117], v[132:133] op_sel_hi:[1,0]
	v_pk_mul_f32 v[114:115], v[114:115], v[132:133] op_sel_hi:[1,0]
	v_pk_mul_f32 v[112:113], v[112:113], v[132:133] op_sel_hi:[1,0]
	v_cmp_ne_u32_e64 s[12:13], 1, v128
	s_andn2_b64 vcc, exec, s[70:71]
	s_mov_b64 s[68:69], -1
	s_cbranch_vccnz .LBB0_398
	v_mov_b64_e32 v[130:131], v[126:127]
	v_mov_b64_e32 v[134:135], v[122:123]
	v_mov_b64_e32 v[138:139], v[118:119]
	v_mov_b64_e32 v[142:143], v[114:115]
	s_and_b64 vcc, exec, s[10:11]
	v_mov_b64_e32 v[128:129], v[124:125]
	v_mov_b64_e32 v[132:133], v[120:121]
	v_mov_b64_e32 v[136:137], v[116:117]
	v_mov_b64_e32 v[140:141], v[112:113]
	s_cbranch_vccnz .LBB0_397
	v_mul_f32_e32 v128, 0xbfb8aa3b, v124
	v_mul_f32_e32 v129, 0xbfb8aa3b, v125
	v_mul_f32_e32 v130, 0xbfb8aa3b, v126
	v_mul_f32_e32 v131, 0xbfb8aa3b, v127
	v_mul_f32_e32 v132, 0xbfb8aa3b, v120
	v_mul_f32_e32 v133, 0xbfb8aa3b, v121
	v_mul_f32_e32 v134, 0xbfb8aa3b, v122
	v_mul_f32_e32 v135, 0xbfb8aa3b, v123
	v_mul_f32_e32 v136, 0xbfb8aa3b, v116
	v_mul_f32_e32 v137, 0xbfb8aa3b, v117
	v_mul_f32_e32 v138, 0xbfb8aa3b, v118
	v_mul_f32_e32 v139, 0xbfb8aa3b, v119
	v_mul_f32_e32 v140, 0xbfb8aa3b, v112
	v_mul_f32_e32 v141, 0xbfb8aa3b, v113
	v_mul_f32_e32 v142, 0xbfb8aa3b, v114
	v_mul_f32_e32 v143, 0xbfb8aa3b, v115
	v_exp_f32_e32 v128, v128
	v_exp_f32_e32 v129, v129
	v_exp_f32_e32 v130, v130
	v_exp_f32_e32 v131, v131
	v_exp_f32_e32 v132, v132
	v_exp_f32_e32 v133, v133
	v_exp_f32_e32 v134, v134
	v_exp_f32_e32 v135, v135
	v_exp_f32_e32 v136, v136
	v_exp_f32_e32 v137, v137
	v_exp_f32_e32 v138, v138
	v_exp_f32_e32 v139, v139
	v_exp_f32_e32 v140, v140
	v_exp_f32_e32 v141, v141
	v_exp_f32_e32 v142, v142
	v_exp_f32_e32 v143, v143
	v_add_f32_e32 v128, 1.0, v128
	v_add_f32_e32 v129, 1.0, v129
	v_add_f32_e32 v130, 1.0, v130
	v_add_f32_e32 v131, 1.0, v131
	v_add_f32_e32 v132, 1.0, v132
	v_add_f32_e32 v133, 1.0, v133
	v_add_f32_e32 v134, 1.0, v134
	v_add_f32_e32 v135, 1.0, v135
	v_add_f32_e32 v136, 1.0, v136
	v_add_f32_e32 v137, 1.0, v137
	v_add_f32_e32 v138, 1.0, v138
	v_add_f32_e32 v139, 1.0, v139
	v_add_f32_e32 v140, 1.0, v140
	v_add_f32_e32 v141, 1.0, v141
	v_add_f32_e32 v142, 1.0, v142
	v_add_f32_e32 v143, 1.0, v143
	v_rcp_f32_e32 v128, v128
	v_rcp_f32_e32 v129, v129
	v_rcp_f32_e32 v130, v130
	v_rcp_f32_e32 v131, v131
	v_rcp_f32_e32 v132, v132
	v_rcp_f32_e32 v133, v133
	v_rcp_f32_e32 v134, v134
	v_rcp_f32_e32 v135, v135
	v_rcp_f32_e32 v136, v136
	v_rcp_f32_e32 v137, v137
	v_rcp_f32_e32 v138, v138
	v_rcp_f32_e32 v139, v139
	v_rcp_f32_e32 v140, v140
	v_rcp_f32_e32 v142, v142
	v_rcp_f32_e32 v143, v143
	v_rcp_f32_e32 v141, v141
	v_pk_mul_f32 v[130:131], v[126:127], v[130:131]
	v_pk_mul_f32 v[128:129], v[124:125], v[128:129]
	v_pk_mul_f32 v[134:135], v[122:123], v[134:135]
	v_pk_mul_f32 v[132:133], v[120:121], v[132:133]
	v_pk_mul_f32 v[138:139], v[118:119], v[138:139]
	v_pk_mul_f32 v[136:137], v[116:117], v[136:137]
	v_pk_mul_f32 v[142:143], v[114:115], v[142:143]
	v_pk_mul_f32 v[140:141], v[112:113], v[140:141]

.LBB0_400:
	s_waitcnt lgkmcnt(5)
	v_add_f32_e32 v112, v226, v227
	v_fmamk_f32 v112, v112, 0x3a800000, v213
	v_rsq_f32_e32 v116, v112
	v_lshlrev_b64 v[112:113], 11, v[198:199]
	v_lshl_add_u64 v[118:119], v[186:187], 0, v[112:113]
	v_cvt_pk_bf16_f32 v112, v128, v129
	v_cvt_pk_bf16_f32 v113, v130, v131
	v_cvt_pk_bf16_f32 v114, v132, v133
	v_cvt_pk_bf16_f32 v115, v134, v135
	global_store_dwordx4 v[118:119], v[112:115], off sc1
	v_pk_mul_f32 v[110:111], v[110:111], v[116:117] op_sel_hi:[1,0]
	v_pk_mul_f32 v[108:109], v[108:109], v[116:117] op_sel_hi:[1,0]
	v_cvt_pk_bf16_f32 v112, v136, v137
	v_cvt_pk_bf16_f32 v113, v138, v139
	v_cvt_pk_bf16_f32 v114, v140, v141
	v_cvt_pk_bf16_f32 v115, v142, v143
	v_pk_mul_f32 v[106:107], v[106:107], v[116:117] op_sel_hi:[1,0]
	v_pk_mul_f32 v[104:105], v[104:105], v[116:117] op_sel_hi:[1,0]
	v_pk_mul_f32 v[102:103], v[102:103], v[116:117] op_sel_hi:[1,0]
	v_pk_mul_f32 v[100:101], v[100:101], v[116:117] op_sel_hi:[1,0]
	v_pk_mul_f32 v[98:99], v[98:99], v[116:117] op_sel_hi:[1,0]
	v_pk_mul_f32 v[96:97], v[96:97], v[116:117] op_sel_hi:[1,0]
	s_and_b64 vcc, exec, s[12:13]
	s_mov_b64 s[68:69], -1
	global_store_dwordx4 v[118:119], v[112:115], off offset:64 sc1
	s_cbranch_vccnz .LBB0_404
	s_nop 0
	v_mov_b64_e32 v[114:115], v[110:111]
	v_mov_b64_e32 v[118:119], v[106:107]
	v_mov_b64_e32 v[122:123], v[102:103]
	v_mov_b64_e32 v[126:127], v[98:99]
	s_and_b64 vcc, exec, s[10:11]
	v_mov_b64_e32 v[112:113], v[108:109]
	v_mov_b64_e32 v[116:117], v[104:105]
	v_mov_b64_e32 v[120:121], v[100:101]
	v_mov_b64_e32 v[124:125], v[96:97]
	s_cbranch_vccnz .LBB0_403
	v_mul_f32_e32 v112, 0xbfb8aa3b, v108
	v_mul_f32_e32 v113, 0xbfb8aa3b, v109
	v_mul_f32_e32 v114, 0xbfb8aa3b, v110
	v_mul_f32_e32 v115, 0xbfb8aa3b, v111
	v_mul_f32_e32 v116, 0xbfb8aa3b, v104
	v_mul_f32_e32 v117, 0xbfb8aa3b, v105
	v_mul_f32_e32 v118, 0xbfb8aa3b, v106
	v_mul_f32_e32 v119, 0xbfb8aa3b, v107
	v_mul_f32_e32 v120, 0xbfb8aa3b, v100
	v_mul_f32_e32 v121, 0xbfb8aa3b, v101
	v_mul_f32_e32 v122, 0xbfb8aa3b, v102
	v_mul_f32_e32 v123, 0xbfb8aa3b, v103
	v_mul_f32_e32 v124, 0xbfb8aa3b, v96
	v_mul_f32_e32 v125, 0xbfb8aa3b, v97
	v_mul_f32_e32 v126, 0xbfb8aa3b, v98
	v_mul_f32_e32 v127, 0xbfb8aa3b, v99
	v_exp_f32_e32 v112, v112
	v_exp_f32_e32 v113, v113
	v_exp_f32_e32 v114, v114
	v_exp_f32_e32 v115, v115
	v_exp_f32_e32 v116, v116
	v_exp_f32_e32 v117, v117
	v_exp_f32_e32 v118, v118
	v_exp_f32_e32 v119, v119
	v_exp_f32_e32 v120, v120
	v_exp_f32_e32 v121, v121
	v_exp_f32_e32 v122, v122
	v_exp_f32_e32 v123, v123
	v_exp_f32_e32 v124, v124
	v_exp_f32_e32 v125, v125
	v_exp_f32_e32 v126, v126
	v_exp_f32_e32 v127, v127
	v_add_f32_e32 v112, 1.0, v112
	v_add_f32_e32 v113, 1.0, v113
	v_add_f32_e32 v114, 1.0, v114
	v_add_f32_e32 v115, 1.0, v115
	v_add_f32_e32 v116, 1.0, v116
	v_add_f32_e32 v117, 1.0, v117
	v_add_f32_e32 v118, 1.0, v118
	v_add_f32_e32 v119, 1.0, v119
	v_add_f32_e32 v120, 1.0, v120
	v_add_f32_e32 v121, 1.0, v121
	v_add_f32_e32 v122, 1.0, v122
	v_add_f32_e32 v123, 1.0, v123
	v_add_f32_e32 v124, 1.0, v124
	v_add_f32_e32 v125, 1.0, v125
	v_add_f32_e32 v126, 1.0, v126
	v_add_f32_e32 v127, 1.0, v127
	v_rcp_f32_e32 v112, v112
	v_rcp_f32_e32 v113, v113
	v_rcp_f32_e32 v114, v114
	v_rcp_f32_e32 v115, v115
	v_rcp_f32_e32 v116, v116
	v_rcp_f32_e32 v117, v117
	v_rcp_f32_e32 v118, v118
	v_rcp_f32_e32 v119, v119
	v_rcp_f32_e32 v120, v120
	v_rcp_f32_e32 v121, v121
	v_rcp_f32_e32 v122, v122
	v_rcp_f32_e32 v123, v123
	v_rcp_f32_e32 v124, v124
	v_rcp_f32_e32 v126, v126
	v_rcp_f32_e32 v127, v127
	v_rcp_f32_e32 v125, v125
	v_pk_mul_f32 v[114:115], v[110:111], v[114:115]
	v_pk_mul_f32 v[112:113], v[108:109], v[112:113]
	v_pk_mul_f32 v[118:119], v[106:107], v[118:119]
	v_pk_mul_f32 v[116:117], v[104:105], v[116:117]
	v_pk_mul_f32 v[122:123], v[102:103], v[122:123]
	v_pk_mul_f32 v[120:121], v[100:101], v[120:121]
	v_pk_mul_f32 v[126:127], v[98:99], v[126:127]
	v_pk_mul_f32 v[124:125], v[96:97], v[124:125]

.LBB0_406:
	s_waitcnt lgkmcnt(4)
	v_add_f32_e32 v96, v224, v225
	v_fmamk_f32 v96, v96, 0x3a800000, v213
	v_rsq_f32_e32 v100, v96
	v_lshlrev_b64 v[96:97], 11, v[194:195]
	v_lshl_add_u64 v[102:103], v[186:187], 0, v[96:97]
	v_cvt_pk_bf16_f32 v96, v112, v113
	v_cvt_pk_bf16_f32 v97, v114, v115
	v_cvt_pk_bf16_f32 v98, v116, v117
	v_cvt_pk_bf16_f32 v99, v118, v119
	global_store_dwordx4 v[102:103], v[96:99], off sc1
	v_pk_mul_f32 v[94:95], v[94:95], v[100:101] op_sel_hi:[1,0]
	v_pk_mul_f32 v[92:93], v[92:93], v[100:101] op_sel_hi:[1,0]
	v_cvt_pk_bf16_f32 v96, v120, v121
	v_cvt_pk_bf16_f32 v97, v122, v123
	v_cvt_pk_bf16_f32 v98, v124, v125
	v_cvt_pk_bf16_f32 v99, v126, v127
	v_pk_mul_f32 v[90:91], v[90:91], v[100:101] op_sel_hi:[1,0]
	v_pk_mul_f32 v[88:89], v[88:89], v[100:101] op_sel_hi:[1,0]
	v_pk_mul_f32 v[86:87], v[86:87], v[100:101] op_sel_hi:[1,0]
	v_pk_mul_f32 v[84:85], v[84:85], v[100:101] op_sel_hi:[1,0]
	v_pk_mul_f32 v[82:83], v[82:83], v[100:101] op_sel_hi:[1,0]
	v_pk_mul_f32 v[80:81], v[80:81], v[100:101] op_sel_hi:[1,0]
	s_and_b64 vcc, exec, s[12:13]
	s_mov_b64 s[68:69], -1
	global_store_dwordx4 v[102:103], v[96:99], off offset:64 sc1
	s_cbranch_vccnz .LBB0_410
	s_nop 0
	v_mov_b64_e32 v[98:99], v[94:95]
	v_mov_b64_e32 v[102:103], v[90:91]
	v_mov_b64_e32 v[106:107], v[86:87]
	v_mov_b64_e32 v[110:111], v[82:83]
	s_and_b64 vcc, exec, s[10:11]
	v_mov_b64_e32 v[96:97], v[92:93]
	v_mov_b64_e32 v[100:101], v[88:89]
	v_mov_b64_e32 v[104:105], v[84:85]
	v_mov_b64_e32 v[108:109], v[80:81]
	s_cbranch_vccnz .LBB0_409
	v_mul_f32_e32 v96, 0xbfb8aa3b, v92
	v_mul_f32_e32 v97, 0xbfb8aa3b, v93
	v_mul_f32_e32 v98, 0xbfb8aa3b, v94
	v_mul_f32_e32 v99, 0xbfb8aa3b, v95
	v_mul_f32_e32 v100, 0xbfb8aa3b, v88
	v_mul_f32_e32 v101, 0xbfb8aa3b, v89
	v_mul_f32_e32 v102, 0xbfb8aa3b, v90
	v_mul_f32_e32 v103, 0xbfb8aa3b, v91
	v_mul_f32_e32 v104, 0xbfb8aa3b, v84
	v_mul_f32_e32 v105, 0xbfb8aa3b, v85
	v_mul_f32_e32 v106, 0xbfb8aa3b, v86
	v_mul_f32_e32 v107, 0xbfb8aa3b, v87
	v_mul_f32_e32 v108, 0xbfb8aa3b, v80
	v_mul_f32_e32 v109, 0xbfb8aa3b, v81
	v_mul_f32_e32 v110, 0xbfb8aa3b, v82
	v_mul_f32_e32 v111, 0xbfb8aa3b, v83
	v_exp_f32_e32 v96, v96
	v_exp_f32_e32 v97, v97
	v_exp_f32_e32 v98, v98
	v_exp_f32_e32 v99, v99
	v_exp_f32_e32 v100, v100
	v_exp_f32_e32 v101, v101
	v_exp_f32_e32 v102, v102
	v_exp_f32_e32 v103, v103
	v_exp_f32_e32 v104, v104
	v_exp_f32_e32 v105, v105
	v_exp_f32_e32 v106, v106
	v_exp_f32_e32 v107, v107
	v_exp_f32_e32 v108, v108
	v_exp_f32_e32 v109, v109
	v_exp_f32_e32 v110, v110
	v_exp_f32_e32 v111, v111
	v_add_f32_e32 v96, 1.0, v96
	v_add_f32_e32 v97, 1.0, v97
	v_add_f32_e32 v98, 1.0, v98
	v_add_f32_e32 v99, 1.0, v99
	v_add_f32_e32 v100, 1.0, v100
	v_add_f32_e32 v101, 1.0, v101
	v_add_f32_e32 v102, 1.0, v102
	v_add_f32_e32 v103, 1.0, v103
	v_add_f32_e32 v104, 1.0, v104
	v_add_f32_e32 v105, 1.0, v105
	v_add_f32_e32 v106, 1.0, v106
	v_add_f32_e32 v107, 1.0, v107
	v_add_f32_e32 v108, 1.0, v108
	v_add_f32_e32 v109, 1.0, v109
	v_add_f32_e32 v110, 1.0, v110
	v_add_f32_e32 v111, 1.0, v111
	v_rcp_f32_e32 v96, v96
	v_rcp_f32_e32 v97, v97
	v_rcp_f32_e32 v98, v98
	v_rcp_f32_e32 v99, v99
	v_rcp_f32_e32 v100, v100
	v_rcp_f32_e32 v101, v101
	v_rcp_f32_e32 v102, v102
	v_rcp_f32_e32 v103, v103
	v_rcp_f32_e32 v104, v104
	v_rcp_f32_e32 v105, v105
	v_rcp_f32_e32 v106, v106
	v_rcp_f32_e32 v107, v107
	v_rcp_f32_e32 v108, v108
	v_rcp_f32_e32 v110, v110
	v_rcp_f32_e32 v111, v111
	v_rcp_f32_e32 v109, v109
	v_pk_mul_f32 v[98:99], v[94:95], v[98:99]
	v_pk_mul_f32 v[96:97], v[92:93], v[96:97]
	v_pk_mul_f32 v[102:103], v[90:91], v[102:103]
	v_pk_mul_f32 v[100:101], v[88:89], v[100:101]
	v_pk_mul_f32 v[106:107], v[86:87], v[106:107]
	v_pk_mul_f32 v[104:105], v[84:85], v[104:105]
	v_pk_mul_f32 v[110:111], v[82:83], v[110:111]
	v_pk_mul_f32 v[108:109], v[80:81], v[108:109]

.LBB0_412:
	s_waitcnt lgkmcnt(3)
	v_add_f32_e32 v80, v222, v223
	v_fmamk_f32 v80, v80, 0x3a800000, v213
	v_rsq_f32_e32 v84, v80
	v_lshlrev_b64 v[80:81], 11, v[192:193]
	v_lshl_add_u64 v[86:87], v[186:187], 0, v[80:81]
	v_cvt_pk_bf16_f32 v80, v96, v97
	v_cvt_pk_bf16_f32 v81, v98, v99
	v_cvt_pk_bf16_f32 v82, v100, v101
	v_cvt_pk_bf16_f32 v83, v102, v103
	global_store_dwordx4 v[86:87], v[80:83], off sc1
	v_pk_mul_f32 v[78:79], v[78:79], v[84:85] op_sel_hi:[1,0]
	v_pk_mul_f32 v[76:77], v[76:77], v[84:85] op_sel_hi:[1,0]
	v_cvt_pk_bf16_f32 v80, v104, v105
	v_cvt_pk_bf16_f32 v81, v106, v107
	v_cvt_pk_bf16_f32 v82, v108, v109
	v_cvt_pk_bf16_f32 v83, v110, v111
	v_pk_mul_f32 v[74:75], v[74:75], v[84:85] op_sel_hi:[1,0]
	v_pk_mul_f32 v[72:73], v[72:73], v[84:85] op_sel_hi:[1,0]
	v_pk_mul_f32 v[70:71], v[70:71], v[84:85] op_sel_hi:[1,0]
	v_pk_mul_f32 v[68:69], v[68:69], v[84:85] op_sel_hi:[1,0]
	v_pk_mul_f32 v[66:67], v[66:67], v[84:85] op_sel_hi:[1,0]
	v_pk_mul_f32 v[64:65], v[64:65], v[84:85] op_sel_hi:[1,0]
	s_and_b64 vcc, exec, s[12:13]
	s_mov_b64 s[68:69], -1
	global_store_dwordx4 v[86:87], v[80:83], off offset:64 sc1
	s_cbranch_vccnz .LBB0_416
	s_nop 0
	v_mov_b64_e32 v[82:83], v[78:79]
	v_mov_b64_e32 v[86:87], v[74:75]
	v_mov_b64_e32 v[90:91], v[70:71]
	v_mov_b64_e32 v[94:95], v[66:67]
	s_and_b64 vcc, exec, s[10:11]
	v_mov_b64_e32 v[80:81], v[76:77]
	v_mov_b64_e32 v[84:85], v[72:73]
	v_mov_b64_e32 v[88:89], v[68:69]
	v_mov_b64_e32 v[92:93], v[64:65]
	s_cbranch_vccnz .LBB0_415
	v_mul_f32_e32 v80, 0xbfb8aa3b, v76
	v_mul_f32_e32 v81, 0xbfb8aa3b, v77
	v_mul_f32_e32 v82, 0xbfb8aa3b, v78
	v_mul_f32_e32 v83, 0xbfb8aa3b, v79
	v_mul_f32_e32 v84, 0xbfb8aa3b, v72
	v_mul_f32_e32 v85, 0xbfb8aa3b, v73
	v_mul_f32_e32 v86, 0xbfb8aa3b, v74
	v_mul_f32_e32 v87, 0xbfb8aa3b, v75
	v_mul_f32_e32 v88, 0xbfb8aa3b, v68
	v_mul_f32_e32 v89, 0xbfb8aa3b, v69
	v_mul_f32_e32 v90, 0xbfb8aa3b, v70
	v_mul_f32_e32 v91, 0xbfb8aa3b, v71
	v_mul_f32_e32 v92, 0xbfb8aa3b, v64
	v_mul_f32_e32 v93, 0xbfb8aa3b, v65
	v_mul_f32_e32 v94, 0xbfb8aa3b, v66
	v_mul_f32_e32 v95, 0xbfb8aa3b, v67
	v_exp_f32_e32 v80, v80
	v_exp_f32_e32 v81, v81
	v_exp_f32_e32 v82, v82
	v_exp_f32_e32 v83, v83
	v_exp_f32_e32 v84, v84
	v_exp_f32_e32 v85, v85
	v_exp_f32_e32 v86, v86
	v_exp_f32_e32 v87, v87
	v_exp_f32_e32 v88, v88
	v_exp_f32_e32 v89, v89
	v_exp_f32_e32 v90, v90
	v_exp_f32_e32 v91, v91
	v_exp_f32_e32 v92, v92
	v_exp_f32_e32 v93, v93
	v_exp_f32_e32 v94, v94
	v_exp_f32_e32 v95, v95
	v_add_f32_e32 v80, 1.0, v80
	v_add_f32_e32 v81, 1.0, v81
	v_add_f32_e32 v82, 1.0, v82
	v_add_f32_e32 v83, 1.0, v83
	v_add_f32_e32 v84, 1.0, v84
	v_add_f32_e32 v85, 1.0, v85
	v_add_f32_e32 v86, 1.0, v86
	v_add_f32_e32 v87, 1.0, v87
	v_add_f32_e32 v88, 1.0, v88
	v_add_f32_e32 v89, 1.0, v89
	v_add_f32_e32 v90, 1.0, v90
	v_add_f32_e32 v91, 1.0, v91
	v_add_f32_e32 v92, 1.0, v92
	v_add_f32_e32 v93, 1.0, v93
	v_add_f32_e32 v94, 1.0, v94
	v_add_f32_e32 v95, 1.0, v95
	v_rcp_f32_e32 v80, v80
	v_rcp_f32_e32 v81, v81
	v_rcp_f32_e32 v82, v82
	v_rcp_f32_e32 v83, v83
	v_rcp_f32_e32 v84, v84
	v_rcp_f32_e32 v85, v85
	v_rcp_f32_e32 v86, v86
	v_rcp_f32_e32 v87, v87
	v_rcp_f32_e32 v88, v88
	v_rcp_f32_e32 v89, v89
	v_rcp_f32_e32 v90, v90
	v_rcp_f32_e32 v91, v91
	v_rcp_f32_e32 v92, v92
	v_rcp_f32_e32 v94, v94
	v_rcp_f32_e32 v95, v95
	v_rcp_f32_e32 v93, v93
	v_pk_mul_f32 v[82:83], v[78:79], v[82:83]
	v_pk_mul_f32 v[80:81], v[76:77], v[80:81]
	v_pk_mul_f32 v[86:87], v[74:75], v[86:87]
	v_pk_mul_f32 v[84:85], v[72:73], v[84:85]
	v_pk_mul_f32 v[90:91], v[70:71], v[90:91]
	v_pk_mul_f32 v[88:89], v[68:69], v[88:89]
	v_pk_mul_f32 v[94:95], v[66:67], v[94:95]
	v_pk_mul_f32 v[92:93], v[64:65], v[92:93]

.LBB0_418:
	s_waitcnt lgkmcnt(2)
	v_add_f32_e32 v64, v220, v221
	v_fmamk_f32 v64, v64, 0x3a800000, v213
	v_rsq_f32_e32 v68, v64
	v_lshlrev_b64 v[64:65], 11, v[190:191]
	v_lshl_add_u64 v[70:71], v[186:187], 0, v[64:65]
	v_cvt_pk_bf16_f32 v64, v80, v81
	v_cvt_pk_bf16_f32 v65, v82, v83
	v_cvt_pk_bf16_f32 v66, v84, v85
	v_cvt_pk_bf16_f32 v67, v86, v87
	global_store_dwordx4 v[70:71], v[64:67], off sc1
	v_pk_mul_f32 v[62:63], v[62:63], v[68:69] op_sel_hi:[1,0]
	v_pk_mul_f32 v[60:61], v[60:61], v[68:69] op_sel_hi:[1,0]
	v_cvt_pk_bf16_f32 v64, v88, v89
	v_cvt_pk_bf16_f32 v65, v90, v91
	v_cvt_pk_bf16_f32 v66, v92, v93
	v_cvt_pk_bf16_f32 v67, v94, v95
	v_pk_mul_f32 v[58:59], v[58:59], v[68:69] op_sel_hi:[1,0]
	v_pk_mul_f32 v[56:57], v[56:57], v[68:69] op_sel_hi:[1,0]
	v_pk_mul_f32 v[54:55], v[54:55], v[68:69] op_sel_hi:[1,0]
	v_pk_mul_f32 v[52:53], v[52:53], v[68:69] op_sel_hi:[1,0]
	v_pk_mul_f32 v[50:51], v[50:51], v[68:69] op_sel_hi:[1,0]
	v_pk_mul_f32 v[48:49], v[48:49], v[68:69] op_sel_hi:[1,0]
	s_and_b64 vcc, exec, s[12:13]
	s_mov_b64 s[68:69], -1
	global_store_dwordx4 v[70:71], v[64:67], off offset:64 sc1
	s_cbranch_vccnz .LBB0_422
	s_nop 0
	v_mov_b64_e32 v[66:67], v[62:63]
	v_mov_b64_e32 v[70:71], v[58:59]
	v_mov_b64_e32 v[74:75], v[54:55]
	v_mov_b64_e32 v[78:79], v[50:51]
	s_and_b64 vcc, exec, s[10:11]
	v_mov_b64_e32 v[64:65], v[60:61]
	v_mov_b64_e32 v[68:69], v[56:57]
	v_mov_b64_e32 v[72:73], v[52:53]
	v_mov_b64_e32 v[76:77], v[48:49]
	s_cbranch_vccnz .LBB0_421
	v_mul_f32_e32 v64, 0xbfb8aa3b, v60
	v_mul_f32_e32 v65, 0xbfb8aa3b, v61
	v_mul_f32_e32 v66, 0xbfb8aa3b, v62
	v_mul_f32_e32 v67, 0xbfb8aa3b, v63
	v_mul_f32_e32 v68, 0xbfb8aa3b, v56
	v_mul_f32_e32 v69, 0xbfb8aa3b, v57
	v_mul_f32_e32 v70, 0xbfb8aa3b, v58
	v_mul_f32_e32 v71, 0xbfb8aa3b, v59
	v_mul_f32_e32 v72, 0xbfb8aa3b, v52
	v_mul_f32_e32 v73, 0xbfb8aa3b, v53
	v_mul_f32_e32 v74, 0xbfb8aa3b, v54
	v_mul_f32_e32 v75, 0xbfb8aa3b, v55
	v_mul_f32_e32 v76, 0xbfb8aa3b, v48
	v_mul_f32_e32 v77, 0xbfb8aa3b, v49
	v_mul_f32_e32 v78, 0xbfb8aa3b, v50
	v_mul_f32_e32 v79, 0xbfb8aa3b, v51
	v_exp_f32_e32 v64, v64
	v_exp_f32_e32 v65, v65
	v_exp_f32_e32 v66, v66
	v_exp_f32_e32 v67, v67
	v_exp_f32_e32 v68, v68
	v_exp_f32_e32 v69, v69
	v_exp_f32_e32 v70, v70
	v_exp_f32_e32 v71, v71
	v_exp_f32_e32 v72, v72
	v_exp_f32_e32 v73, v73
	v_exp_f32_e32 v74, v74
	v_exp_f32_e32 v75, v75
	v_exp_f32_e32 v76, v76
	v_exp_f32_e32 v77, v77
	v_exp_f32_e32 v78, v78
	v_exp_f32_e32 v79, v79
	v_add_f32_e32 v64, 1.0, v64
	v_add_f32_e32 v65, 1.0, v65
	v_add_f32_e32 v66, 1.0, v66
	v_add_f32_e32 v67, 1.0, v67
	v_add_f32_e32 v68, 1.0, v68
	v_add_f32_e32 v69, 1.0, v69
	v_add_f32_e32 v70, 1.0, v70
	v_add_f32_e32 v71, 1.0, v71
	v_add_f32_e32 v72, 1.0, v72
	v_add_f32_e32 v73, 1.0, v73
	v_add_f32_e32 v74, 1.0, v74
	v_add_f32_e32 v75, 1.0, v75
	v_add_f32_e32 v76, 1.0, v76
	v_add_f32_e32 v77, 1.0, v77
	v_add_f32_e32 v78, 1.0, v78
	v_add_f32_e32 v79, 1.0, v79
	v_rcp_f32_e32 v64, v64
	v_rcp_f32_e32 v65, v65
	v_rcp_f32_e32 v66, v66
	v_rcp_f32_e32 v67, v67
	v_rcp_f32_e32 v68, v68
	v_rcp_f32_e32 v69, v69
	v_rcp_f32_e32 v70, v70
	v_rcp_f32_e32 v71, v71
	v_rcp_f32_e32 v72, v72
	v_rcp_f32_e32 v73, v73
	v_rcp_f32_e32 v74, v74
	v_rcp_f32_e32 v75, v75
	v_rcp_f32_e32 v76, v76
	v_rcp_f32_e32 v78, v78
	v_rcp_f32_e32 v79, v79
	v_rcp_f32_e32 v77, v77
	v_pk_mul_f32 v[66:67], v[62:63], v[66:67]
	v_pk_mul_f32 v[64:65], v[60:61], v[64:65]
	v_pk_mul_f32 v[70:71], v[58:59], v[70:71]
	v_pk_mul_f32 v[68:69], v[56:57], v[68:69]
	v_pk_mul_f32 v[74:75], v[54:55], v[74:75]
	v_pk_mul_f32 v[72:73], v[52:53], v[72:73]
	v_pk_mul_f32 v[78:79], v[50:51], v[78:79]
	v_pk_mul_f32 v[76:77], v[48:49], v[76:77]

.LBB0_424:
	s_waitcnt lgkmcnt(1)
	v_add_f32_e32 v48, v218, v219
	v_fmamk_f32 v48, v48, 0x3a800000, v213
	v_rsq_f32_e32 v52, v48
	v_lshlrev_b64 v[48:49], 11, v[188:189]
	v_lshl_add_u64 v[54:55], v[186:187], 0, v[48:49]
	v_cvt_pk_bf16_f32 v48, v64, v65
	v_cvt_pk_bf16_f32 v49, v66, v67
	v_cvt_pk_bf16_f32 v50, v68, v69
	v_cvt_pk_bf16_f32 v51, v70, v71
	global_store_dwordx4 v[54:55], v[48:51], off sc1
	v_pk_mul_f32 v[30:31], v[30:31], v[52:53] op_sel_hi:[1,0]
	v_pk_mul_f32 v[28:29], v[28:29], v[52:53] op_sel_hi:[1,0]
	v_cvt_pk_bf16_f32 v48, v72, v73
	v_cvt_pk_bf16_f32 v49, v74, v75
	v_cvt_pk_bf16_f32 v50, v76, v77
	v_cvt_pk_bf16_f32 v51, v78, v79
	v_pk_mul_f32 v[26:27], v[26:27], v[52:53] op_sel_hi:[1,0]
	v_pk_mul_f32 v[24:25], v[24:25], v[52:53] op_sel_hi:[1,0]
	v_pk_mul_f32 v[22:23], v[22:23], v[52:53] op_sel_hi:[1,0]
	v_pk_mul_f32 v[20:21], v[20:21], v[52:53] op_sel_hi:[1,0]
	v_pk_mul_f32 v[18:19], v[18:19], v[52:53] op_sel_hi:[1,0]
	v_pk_mul_f32 v[16:17], v[16:17], v[52:53] op_sel_hi:[1,0]
	s_and_b64 vcc, exec, s[12:13]
	s_mov_b64 s[68:69], -1
	global_store_dwordx4 v[54:55], v[48:51], off offset:64 sc1
	s_cbranch_vccnz .LBB0_428
	s_nop 0
	v_mov_b64_e32 v[50:51], v[30:31]
	v_mov_b64_e32 v[54:55], v[26:27]
	v_mov_b64_e32 v[58:59], v[22:23]
	v_mov_b64_e32 v[62:63], v[18:19]
	s_and_b64 vcc, exec, s[10:11]
	v_mov_b64_e32 v[48:49], v[28:29]
	v_mov_b64_e32 v[52:53], v[24:25]
	v_mov_b64_e32 v[56:57], v[20:21]
	v_mov_b64_e32 v[60:61], v[16:17]
	s_cbranch_vccnz .LBB0_427
	v_mul_f32_e32 v48, 0xbfb8aa3b, v28
	v_mul_f32_e32 v49, 0xbfb8aa3b, v29
	v_mul_f32_e32 v50, 0xbfb8aa3b, v30
	v_mul_f32_e32 v51, 0xbfb8aa3b, v31
	v_mul_f32_e32 v52, 0xbfb8aa3b, v24
	v_mul_f32_e32 v53, 0xbfb8aa3b, v25
	v_mul_f32_e32 v54, 0xbfb8aa3b, v26
	v_mul_f32_e32 v55, 0xbfb8aa3b, v27
	v_mul_f32_e32 v56, 0xbfb8aa3b, v20
	v_mul_f32_e32 v57, 0xbfb8aa3b, v21
	v_mul_f32_e32 v58, 0xbfb8aa3b, v22
	v_mul_f32_e32 v59, 0xbfb8aa3b, v23
	v_mul_f32_e32 v60, 0xbfb8aa3b, v16
	v_mul_f32_e32 v61, 0xbfb8aa3b, v17
	v_mul_f32_e32 v62, 0xbfb8aa3b, v18
	v_mul_f32_e32 v63, 0xbfb8aa3b, v19
	v_exp_f32_e32 v48, v48
	v_exp_f32_e32 v49, v49
	v_exp_f32_e32 v50, v50
	v_exp_f32_e32 v51, v51
	v_exp_f32_e32 v52, v52
	v_exp_f32_e32 v53, v53
	v_exp_f32_e32 v54, v54
	v_exp_f32_e32 v55, v55
	v_exp_f32_e32 v56, v56
	v_exp_f32_e32 v57, v57
	v_exp_f32_e32 v58, v58
	v_exp_f32_e32 v59, v59
	v_exp_f32_e32 v60, v60
	v_exp_f32_e32 v61, v61
	v_exp_f32_e32 v62, v62
	v_exp_f32_e32 v63, v63
	v_add_f32_e32 v48, 1.0, v48
	v_add_f32_e32 v49, 1.0, v49
	v_add_f32_e32 v50, 1.0, v50
	v_add_f32_e32 v51, 1.0, v51
	v_add_f32_e32 v52, 1.0, v52
	v_add_f32_e32 v53, 1.0, v53
	v_add_f32_e32 v54, 1.0, v54
	v_add_f32_e32 v55, 1.0, v55
	v_add_f32_e32 v56, 1.0, v56
	v_add_f32_e32 v57, 1.0, v57
	v_add_f32_e32 v58, 1.0, v58
	v_add_f32_e32 v59, 1.0, v59
	v_add_f32_e32 v60, 1.0, v60
	v_add_f32_e32 v61, 1.0, v61
	v_add_f32_e32 v62, 1.0, v62
	v_add_f32_e32 v63, 1.0, v63
	v_rcp_f32_e32 v48, v48
	v_rcp_f32_e32 v49, v49
	v_rcp_f32_e32 v50, v50
	v_rcp_f32_e32 v51, v51
	v_rcp_f32_e32 v52, v52
	v_rcp_f32_e32 v53, v53
	v_rcp_f32_e32 v54, v54
	v_rcp_f32_e32 v55, v55
	v_rcp_f32_e32 v56, v56
	v_rcp_f32_e32 v57, v57
	v_rcp_f32_e32 v58, v58
	v_rcp_f32_e32 v59, v59
	v_rcp_f32_e32 v60, v60
	v_rcp_f32_e32 v62, v62
	v_rcp_f32_e32 v63, v63
	v_rcp_f32_e32 v61, v61
	v_pk_mul_f32 v[50:51], v[30:31], v[50:51]
	v_pk_mul_f32 v[48:49], v[28:29], v[48:49]
	v_pk_mul_f32 v[54:55], v[26:27], v[54:55]
	v_pk_mul_f32 v[52:53], v[24:25], v[52:53]
	v_pk_mul_f32 v[58:59], v[22:23], v[58:59]
	v_pk_mul_f32 v[56:57], v[20:21], v[56:57]
	v_pk_mul_f32 v[62:63], v[18:19], v[62:63]
	v_pk_mul_f32 v[60:61], v[16:17], v[60:61]

.LBB0_430:
	s_waitcnt lgkmcnt(0)
	v_add_f32_e32 v16, v216, v217
	v_fmamk_f32 v16, v16, 0x3a800000, v213
	v_rsq_f32_e32 v20, v16
	v_lshlrev_b64 v[16:17], 11, v[184:185]
	v_lshl_add_u64 v[22:23], v[186:187], 0, v[16:17]
	v_cvt_pk_bf16_f32 v16, v48, v49
	v_cvt_pk_bf16_f32 v17, v50, v51
	v_cvt_pk_bf16_f32 v18, v52, v53
	v_cvt_pk_bf16_f32 v19, v54, v55
	global_store_dwordx4 v[22:23], v[16:19], off sc1
	v_pk_mul_f32 v[14:15], v[14:15], v[20:21] op_sel_hi:[1,0]
	v_pk_mul_f32 v[12:13], v[12:13], v[20:21] op_sel_hi:[1,0]
	v_cvt_pk_bf16_f32 v16, v56, v57
	v_cvt_pk_bf16_f32 v17, v58, v59
	v_cvt_pk_bf16_f32 v18, v60, v61
	v_cvt_pk_bf16_f32 v19, v62, v63
	v_pk_mul_f32 v[10:11], v[10:11], v[20:21] op_sel_hi:[1,0]
	v_pk_mul_f32 v[8:9], v[8:9], v[20:21] op_sel_hi:[1,0]
	v_pk_mul_f32 v[6:7], v[6:7], v[20:21] op_sel_hi:[1,0]
	v_pk_mul_f32 v[4:5], v[4:5], v[20:21] op_sel_hi:[1,0]
	v_pk_mul_f32 v[2:3], v[2:3], v[20:21] op_sel_hi:[1,0]
	v_pk_mul_f32 v[0:1], v[0:1], v[20:21] op_sel_hi:[1,0]
	s_and_b64 vcc, exec, s[12:13]
	s_mov_b64 s[12:13], -1
	global_store_dwordx4 v[22:23], v[16:19], off offset:64 sc1
	s_cbranch_vccnz .LBB0_434
	s_nop 0
	v_mov_b64_e32 v[18:19], v[14:15]
	v_mov_b64_e32 v[22:23], v[10:11]
	v_mov_b64_e32 v[26:27], v[6:7]
	v_mov_b64_e32 v[30:31], v[2:3]
	s_and_b64 vcc, exec, s[10:11]
	v_mov_b64_e32 v[16:17], v[12:13]
	v_mov_b64_e32 v[20:21], v[8:9]
	v_mov_b64_e32 v[24:25], v[4:5]
	v_mov_b64_e32 v[28:29], v[0:1]
	s_cbranch_vccnz .LBB0_433
	v_mul_f32_e32 v16, 0xbfb8aa3b, v12
	v_mul_f32_e32 v17, 0xbfb8aa3b, v13
	v_mul_f32_e32 v18, 0xbfb8aa3b, v14
	v_mul_f32_e32 v19, 0xbfb8aa3b, v15
	v_mul_f32_e32 v20, 0xbfb8aa3b, v8
	v_mul_f32_e32 v21, 0xbfb8aa3b, v9
	v_mul_f32_e32 v22, 0xbfb8aa3b, v10
	v_mul_f32_e32 v23, 0xbfb8aa3b, v11
	v_mul_f32_e32 v24, 0xbfb8aa3b, v4
	v_mul_f32_e32 v25, 0xbfb8aa3b, v5
	v_mul_f32_e32 v26, 0xbfb8aa3b, v6
	v_mul_f32_e32 v27, 0xbfb8aa3b, v7
	v_mul_f32_e32 v28, 0xbfb8aa3b, v0
	v_mul_f32_e32 v29, 0xbfb8aa3b, v1
	v_mul_f32_e32 v30, 0xbfb8aa3b, v2
	v_mul_f32_e32 v31, 0xbfb8aa3b, v3
	v_exp_f32_e32 v16, v16
	v_exp_f32_e32 v17, v17
	v_exp_f32_e32 v18, v18
	v_exp_f32_e32 v19, v19
	v_exp_f32_e32 v20, v20
	v_exp_f32_e32 v21, v21
	v_exp_f32_e32 v22, v22
	v_exp_f32_e32 v23, v23
	v_exp_f32_e32 v24, v24
	v_exp_f32_e32 v25, v25
	v_exp_f32_e32 v26, v26
	v_exp_f32_e32 v27, v27
	v_exp_f32_e32 v28, v28
	v_exp_f32_e32 v29, v29
	v_exp_f32_e32 v30, v30
	v_exp_f32_e32 v31, v31
	v_add_f32_e32 v16, 1.0, v16
	v_add_f32_e32 v17, 1.0, v17
	v_add_f32_e32 v18, 1.0, v18
	v_add_f32_e32 v19, 1.0, v19
	v_add_f32_e32 v20, 1.0, v20
	v_add_f32_e32 v21, 1.0, v21
	v_add_f32_e32 v22, 1.0, v22
	v_add_f32_e32 v23, 1.0, v23
	v_add_f32_e32 v24, 1.0, v24
	v_add_f32_e32 v25, 1.0, v25
	v_add_f32_e32 v26, 1.0, v26
	v_add_f32_e32 v27, 1.0, v27
	v_add_f32_e32 v28, 1.0, v28
	v_add_f32_e32 v29, 1.0, v29
	v_add_f32_e32 v30, 1.0, v30
	v_add_f32_e32 v31, 1.0, v31
	v_rcp_f32_e32 v16, v16
	v_rcp_f32_e32 v17, v17
	v_rcp_f32_e32 v18, v18
	v_rcp_f32_e32 v19, v19
	v_rcp_f32_e32 v20, v20
	v_rcp_f32_e32 v21, v21
	v_rcp_f32_e32 v22, v22
	v_rcp_f32_e32 v23, v23
	v_rcp_f32_e32 v24, v24
	v_rcp_f32_e32 v25, v25
	v_rcp_f32_e32 v26, v26
	v_rcp_f32_e32 v27, v27
	v_rcp_f32_e32 v28, v28
	v_rcp_f32_e32 v30, v30
	v_rcp_f32_e32 v31, v31
	v_rcp_f32_e32 v29, v29
	v_pk_mul_f32 v[18:19], v[14:15], v[18:19]
	v_pk_mul_f32 v[16:17], v[12:13], v[16:17]
	v_pk_mul_f32 v[22:23], v[10:11], v[22:23]
	v_pk_mul_f32 v[20:21], v[8:9], v[20:21]
	v_pk_mul_f32 v[26:27], v[6:7], v[26:27]
	v_pk_mul_f32 v[24:25], v[4:5], v[24:25]
	v_pk_mul_f32 v[30:31], v[2:3], v[30:31]
	v_pk_mul_f32 v[28:29], v[0:1], v[28:29]

.LBB0_436:
	v_lshlrev_b64 v[0:1], 11, v[182:183]
	v_lshl_add_u64 v[4:5], v[186:187], 0, v[0:1]
	v_cvt_pk_bf16_f32 v0, v16, v17
	v_cvt_pk_bf16_f32 v1, v18, v19
	v_cvt_pk_bf16_f32 v2, v20, v21
	v_cvt_pk_bf16_f32 v3, v22, v23
	s_andn2_b64 vcc, exec, s[8:9]
	s_mov_b64 s[8:9], -1
	global_store_dwordx4 v[4:5], v[0:3], off sc1
	s_nop 1
	v_cvt_pk_bf16_f32 v0, v24, v25
	v_cvt_pk_bf16_f32 v1, v26, v27
	v_cvt_pk_bf16_f32 v2, v28, v29
	v_cvt_pk_bf16_f32 v3, v30, v31
	global_store_dwordx4 v[4:5], v[0:3], off offset:64 sc1
	s_cbranch_vccnz .LBB0_366
	s_andn2_b64 vcc, exec, s[0:1]
	s_cbranch_vccnz .LBB0_365
	s_barrier
	s_branch .LBB0_365

.LBB0_443:
	v_add_u32_e32 v10, s15, v171
	v_add_u32_e32 v34, 16, v10
	v_add_u32_e32 v38, 32, v10
	v_ashrrev_i32_e32 v11, 31, v10
	v_ashrrev_i32_e32 v35, 31, v34
	v_ashrrev_i32_e32 v39, 31, v38
	v_lshlrev_b64 v[50:51], 11, v[10:11]
	v_lshlrev_b64 v[54:55], 11, v[34:35]
	v_lshlrev_b64 v[58:59], 11, v[38:39]
	v_lshl_add_u64 v[30:31], v[4:5], 0, v[50:51]
	v_lshl_add_u64 v[34:35], v[4:5], 0, v[54:55]
	v_lshl_add_u64 v[38:39], v[4:5], 0, v[58:59]
	global_load_dwordx4 v[26:29], v[2:3], off
	v_add_u32_e32 v10, 48, v10
	global_load_dwordx4 v[30:33], v[30:31], off
	v_ashrrev_i32_e32 v11, 31, v10
	global_load_dwordx4 v[34:37], v[34:35], off
	v_lshlrev_b64 v[10:11], 11, v[10:11]
	global_load_dwordx4 v[38:41], v[38:39], off
	v_lshl_add_u64 v[42:43], v[4:5], 0, v[10:11]
	global_load_dwordx4 v[42:45], v[42:43], off
	s_nop 0
	global_load_dwordx4 v[46:49], v[2:3], off offset:64
	v_lshl_add_u64 v[66:67], s[36:37], 0, v[50:51]
	v_lshl_add_u64 v[68:69], s[36:37], 0, v[54:55]
	v_lshl_add_u64 v[50:51], v[66:67], 0, v[0:1]
	v_lshl_add_u64 v[54:55], v[68:69], 0, v[0:1]
	v_lshl_add_u64 v[70:71], s[36:37], 0, v[58:59]
	global_load_dwordx4 v[50:53], v[50:51], off
	v_lshl_add_u64 v[58:59], v[70:71], 0, v[0:1]
	global_load_dwordx4 v[54:57], v[54:55], off
	v_lshl_add_u64 v[10:11], s[36:37], 0, v[10:11]
	global_load_dwordx4 v[58:61], v[58:59], off
	v_lshl_add_u64 v[62:63], v[10:11], 0, v[0:1]
	v_lshl_add_u64 v[72:73], v[68:69], 0, v[6:7]
	s_waitcnt vmcnt(7)
	v_mfma_f32_16x16x32_bf16 v[30:33], v[30:33], v[26:29], 0
	s_waitcnt vmcnt(6)
	v_mfma_f32_16x16x32_bf16 v[34:37], v[34:37], v[26:29], 0
	s_waitcnt vmcnt(5)
	v_mfma_f32_16x16x32_bf16 v[38:41], v[38:41], v[26:29], 0
	s_waitcnt vmcnt(4)
	v_mfma_f32_16x16x32_bf16 v[26:29], v[42:45], v[26:29], 0
	global_load_dwordx4 v[42:45], v[62:63], off
	v_lshl_add_u64 v[62:63], v[66:67], 0, v[6:7]
	v_lshl_add_u64 v[66:67], v[66:67], 0, v[8:9]
	s_waitcnt vmcnt(3)
	v_mfma_f32_16x16x32_bf16 v[30:33], v[50:53], v[46:49], v[30:33]
	global_load_dwordx4 v[50:53], v[62:63], off
	s_nop 0
	global_load_dwordx4 v[62:65], v[2:3], off offset:128
	s_waitcnt vmcnt(4)
	v_mfma_f32_16x16x32_bf16 v[34:37], v[54:57], v[46:49], v[34:37]
	global_load_dwordx4 v[54:57], v[72:73], off
	v_lshl_add_u64 v[72:73], v[70:71], 0, v[6:7]
	s_waitcnt vmcnt(4)
	v_mfma_f32_16x16x32_bf16 v[38:41], v[58:61], v[46:49], v[38:41]
	global_load_dwordx4 v[58:61], v[72:73], off
	v_lshl_add_u64 v[72:73], v[10:11], 0, v[6:7]
	v_lshl_add_u64 v[10:11], v[10:11], 0, v[8:9]
	s_waitcnt vmcnt(2)
	v_mfma_f32_16x16x32_bf16 v[30:33], v[50:53], v[62:65], v[30:33]
	v_mfma_f32_16x16x32_bf16 v[26:29], v[42:45], v[46:49], v[26:29]
	global_load_dwordx4 v[42:45], v[72:73], off
	global_load_dwordx4 v[46:49], v[2:3], off offset:192
	global_load_dwordx4 v[50:53], v[66:67], off
	s_waitcnt vmcnt(4)
	v_mfma_f32_16x16x32_bf16 v[34:37], v[54:57], v[62:65], v[34:37]
	s_waitcnt vmcnt(3)
	v_mfma_f32_16x16x32_bf16 v[38:41], v[58:61], v[62:65], v[38:41]
	s_waitcnt vmcnt(2)
	v_mfma_f32_16x16x32_bf16 v[26:29], v[42:45], v[62:65], v[26:29]
	global_load_dwordx4 v[42:45], v[10:11], off
	v_lshl_add_u64 v[66:67], v[68:69], 0, v[8:9]
	global_load_dwordx4 v[54:57], v[66:67], off
	v_lshl_add_u64 v[66:67], v[70:71], 0, v[8:9]
	global_load_dwordx4 v[58:61], v[66:67], off
	v_add_u32_e32 v10, s15, v204
	v_ashrrev_i32_e32 v11, 31, v10
	s_waitcnt vmcnt(3)
	v_mfma_f32_16x16x32_bf16 v[30:33], v[50:53], v[46:49], v[30:33]
	v_lshlrev_b64 v[50:51], 6, v[10:11]
	v_lshl_add_u64 v[66:67], s[60:61], 0, v[50:51]
	global_load_dwordx4 v[50:53], v[66:67], off
	v_lshl_add_u64 v[10:11], v[10:11], 2, s[38:39]
	s_waitcnt vmcnt(3)
	v_mfma_f32_16x16x32_bf16 v[26:29], v[42:45], v[46:49], v[26:29]
	s_waitcnt vmcnt(0)
	v_add_f32_e32 v25, v50, v51
	v_mfma_f32_16x16x32_bf16 v[34:37], v[54:57], v[46:49], v[34:37]
	global_load_dwordx4 v[54:57], v[66:67], off offset:16
	global_load_dwordx4 v[62:65], v[66:67], off offset:32
	v_mfma_f32_16x16x32_bf16 v[38:41], v[58:61], v[46:49], v[38:41]
	global_load_dwordx4 v[58:61], v[66:67], off offset:48
	ds_write2_b32 v19, v30, v31 offset1:16
	ds_write2_b32 v19, v32, v33 offset0:32 offset1:48
	s_nop 1
	ds_write2_b32 v22, v34, v35 offset1:16
	ds_write2_b32 v22, v36, v37 offset0:32 offset1:48
	s_nop 0
	ds_write2_b32 v23, v38, v39 offset1:16
	ds_write2_b32 v23, v40, v41 offset0:32 offset1:48
	ds_write2_b32 v24, v26, v27 offset1:16
	ds_write2_b32 v24, v28, v29 offset0:32 offset1:48
	s_waitcnt lgkmcnt(0)
	s_barrier
	global_load_dword v34, v1, s[40:41]
	v_add_f32_e32 v26, v52, v53
	v_add_f32_e32 v25, v25, v26
	s_waitcnt vmcnt(3)
	v_add_f32_e32 v27, v54, v55
	v_add_f32_e32 v28, v56, v57
	s_waitcnt vmcnt(2)
	v_add_f32_e32 v29, v62, v63
	v_add_f32_e32 v30, v64, v65
	v_add_f32_e32 v26, v27, v28
	s_waitcnt vmcnt(1)
	v_add_f32_e32 v31, v58, v59
	v_add_f32_e32 v32, v60, v61
	v_add_f32_e32 v27, v29, v30
	v_add_f32_e32 v25, v25, v26
	v_add_f32_e32 v28, v31, v32
	v_add_f32_e32 v25, v25, v27
	v_add_f32_e32 v25, v25, v28
	v_fmamk_f32 v25, v25, 0x3a800000, v20
	v_mul_f32_e32 v26, 0x4f800000, v25
	v_cmp_gt_f32_e32 vcc, s57, v25
	s_nop 1
	v_cndmask_b32_e32 v25, v25, v26, vcc
	v_sqrt_f32_e32 v26, v25
	s_nop 0
	v_add_u32_e32 v27, -1, v26
	v_add_u32_e32 v28, 1, v26
	v_fma_f32 v29, -v27, v26, v25
	v_fma_f32 v30, -v28, v26, v25
	v_cmp_ge_f32_e64 s[22:23], 0, v29
	s_nop 1
	v_cndmask_b32_e64 v26, v26, v27, s[22:23]
	v_cmp_lt_f32_e64 s[22:23], 0, v30
	s_nop 1
	v_cndmask_b32_e64 v26, v26, v28, s[22:23]
	v_mul_f32_e32 v27, 0x37800000, v26
	v_cndmask_b32_e32 v26, v26, v27, vcc
	v_cmp_class_f32_e32 vcc, v25, v21
	s_nop 1
	v_cndmask_b32_e32 v25, v26, v25, vcc
	v_div_scale_f32 v35, s[22:23], v25, v25, 1.0
	v_rcp_f32_e32 v37, v35
	ds_read2st64_b32 v[26:27], v12 offset1:16
	ds_read2st64_b32 v[28:29], v12 offset0:32 offset1:48
	ds_read2st64_b32 v[30:31], v12 offset0:64 offset1:80
	ds_read2st64_b32 v[32:33], v12 offset0:96 offset1:112
	v_div_scale_f32 v36, vcc, 1.0, v25, 1.0
	v_fma_f32 v38, -v35, v37, 1.0
	s_waitcnt lgkmcnt(3)
	v_add_f32_e32 v26, 0, v26
	v_fmac_f32_e32 v37, v38, v37
	v_add_f32_e32 v26, v26, v27
	v_mul_f32_e32 v38, v36, v37
	s_waitcnt lgkmcnt(2)
	v_add_f32_e32 v26, v26, v28
	v_fma_f32 v39, -v35, v38, v36
	v_add_f32_e32 v26, v26, v29
	v_fmac_f32_e32 v38, v39, v37
	s_waitcnt lgkmcnt(1)
	v_add_f32_e32 v26, v26, v30
	v_fma_f32 v27, -v35, v38, v36
	v_add_f32_e32 v26, v26, v31
	v_div_fmas_f32 v27, v27, v37, v38
	s_waitcnt lgkmcnt(0)
	v_add_f32_e32 v26, v26, v32
	v_div_fixup_f32 v25, v27, v25, 1.0
	v_add_f32_e32 v26, v26, v33
	s_waitcnt vmcnt(0)
	v_fmac_f32_e32 v34, v25, v26
	v_mul_f32_e64 v26, |v34|, s64
	v_exp_f32_e32 v26, v26
	v_min_f32_e32 v27, 0, v34
	v_lshl_add_u64 v[28:29], v[10:11], 0, s[58:59]
	v_add_f32_e32 v26, 1.0, v26
	v_log_f32_e32 v26, v26
	s_nop 0
	v_fmac_f32_e32 v27, 0xbf317218, v26
	ds_bpermute_b32 v26, v13, v27
	s_waitcnt lgkmcnt(0)
	v_add_f32_e32 v26, v27, v26
	v_cndmask_b32_e64 v26, v26, v27, s[8:9]
	ds_bpermute_b32 v27, v14, v26
	s_waitcnt lgkmcnt(0)
	v_add_f32_e32 v27, v26, v27
	v_cndmask_b32_e64 v26, v27, v26, s[10:11]
	ds_bpermute_b32 v27, v15, v26
	s_waitcnt lgkmcnt(0)
	v_add_f32_e32 v27, v26, v27
	v_cndmask_b32_e64 v26, v27, v26, s[12:13]
	ds_bpermute_b32 v27, v16, v26
	s_waitcnt lgkmcnt(0)
	v_add_f32_e32 v27, v26, v27
	v_cndmask_b32_e64 v26, v27, v26, s[16:17]
	ds_bpermute_b32 v27, v17, v26
	s_waitcnt lgkmcnt(0)
	v_add_f32_e32 v27, v26, v27
	v_cndmask_b32_e64 v27, v27, v26, s[18:19]
	ds_bpermute_b32 v26, v18, v27
	s_waitcnt lgkmcnt(0)
	v_add_f32_e32 v26, v27, v26
	v_cndmask_b32_e64 v27, v26, v27, s[20:21]
	global_store_dword v[28:29], v27, off sc1
	s_and_saveexec_b64 s[22:23], s[0:1]
	s_cbranch_execz .LBB0_445
	s_add_i32 s66, s14, s65
	s_ashr_i32 s67, s66, 31
	s_lshl_b64 s[66:67], s[66:67], 2
	s_add_u32 s66, s74, s66
	s_addc_u32 s67, s75, s67
	global_store_dword v1, v26, s[66:67] sc1
.LBB0_445:
	s_or_b64 exec, exec, s[22:23]
	global_load_dword v34, v1, s[40:41] offset:4
	v_add_u32_e32 v32, 4, v12
	ds_read2st64_b32 v[26:27], v32 offset1:16
	ds_read2st64_b32 v[28:29], v32 offset0:32 offset1:48
	ds_read2st64_b32 v[30:31], v32 offset0:64 offset1:80
	ds_read2st64_b32 v[32:33], v32 offset0:96 offset1:112
	v_lshl_add_u64 v[10:11], v[10:11], 0, s[62:63]
	s_waitcnt lgkmcnt(3)
	v_add_f32_e32 v26, 0, v26
	v_add_f32_e32 v26, v26, v27
	s_waitcnt lgkmcnt(2)
	v_add_f32_e32 v26, v26, v28
	v_add_f32_e32 v26, v26, v29
	s_waitcnt lgkmcnt(1)
	v_add_f32_e32 v26, v26, v30
	v_add_f32_e32 v26, v26, v31
	s_waitcnt lgkmcnt(0)
	v_add_f32_e32 v26, v26, v32
	v_add_f32_e32 v26, v26, v33
	s_waitcnt vmcnt(0)
	v_fmac_f32_e32 v34, v25, v26
	v_mul_f32_e64 v25, |v34|, s64
	v_exp_f32_e32 v25, v25
	v_min_f32_e32 v26, 0, v34
	v_add_f32_e32 v25, 1.0, v25
	v_log_f32_e32 v25, v25
	s_nop 0
	v_fmac_f32_e32 v26, 0xbf317218, v25
	ds_bpermute_b32 v25, v13, v26
	s_waitcnt lgkmcnt(0)
	v_add_f32_e32 v25, v26, v25
	v_cndmask_b32_e64 v25, v25, v26, s[8:9]
	ds_bpermute_b32 v26, v14, v25
	s_waitcnt lgkmcnt(0)
	v_add_f32_e32 v26, v25, v26
	v_cndmask_b32_e64 v25, v26, v25, s[10:11]
	ds_bpermute_b32 v26, v15, v25
	s_waitcnt lgkmcnt(0)
	v_add_f32_e32 v26, v25, v26
	v_cndmask_b32_e64 v25, v26, v25, s[12:13]
	ds_bpermute_b32 v26, v16, v25
	s_waitcnt lgkmcnt(0)
	v_add_f32_e32 v26, v25, v26
	v_cndmask_b32_e64 v25, v26, v25, s[16:17]
	ds_bpermute_b32 v26, v17, v25
	s_waitcnt lgkmcnt(0)
	v_add_f32_e32 v26, v25, v26
	v_cndmask_b32_e64 v26, v26, v25, s[18:19]
	ds_bpermute_b32 v25, v18, v26
	s_waitcnt lgkmcnt(0)
	v_add_f32_e32 v25, v26, v25
	v_cndmask_b32_e64 v26, v25, v26, s[20:21]
	global_store_dword v[10:11], v26, off sc1
	s_and_saveexec_b64 s[22:23], s[0:1]
	s_cbranch_execz .LBB0_442
	s_add_i32 s33, s14, s65
	s_add_i32 s66, s33, 0x100
	s_ashr_i32 s67, s66, 31
	s_lshl_b64 s[66:67], s[66:67], 2
	s_add_u32 s66, s74, s66
	s_addc_u32 s67, s75, s67
	global_store_dword v1, v25, s[66:67] sc1
	s_branch .LBB0_442

.LBB0_500:
	s_andn2_saveexec_b64 s[14:15], s[16:17]
	s_cbranch_execz .LBB0_520
	s_mov_b64 s[16:17], exec
	s_waitcnt lgkmcnt(0)
	s_waitcnt vmcnt(0)
	v_mbcnt_lo_u32_b32 v1, s16, 0
	v_mbcnt_hi_u32_b32 v1, s17, v1
	v_cmp_eq_u32_e32 vcc, 0, v1
	s_and_saveexec_b64 s[20:21], vcc
	s_cbranch_execz .LBB0_503
	s_bcnt1_i32_b64 s14, s[16:17]
	v_mov_b32_e32 v3, 0x3000
	v_mov_b32_e32 v6, s14
	global_atomic_add v3, v3, v6, s[52:53] offset:1024 sc0

.LBB0_650:
	v_add_f32_e32 v0, v64, v65
	v_add_f32_e32 v0, v66, v0
	v_add_f32_e32 v0, v67, v0
	v_add_f32_e32 v0, v68, v0
	v_add_f32_e32 v0, v69, v0
	v_add_f32_e32 v0, v70, v0
	v_add_f32_e32 v0, v71, v0
	v_add_f32_e32 v0, v72, v0
	v_add_f32_e32 v0, v73, v0
	v_add_f32_e32 v0, v74, v0
	v_add_f32_e32 v0, v75, v0
	v_add_f32_e32 v0, v76, v0
	v_add_f32_e32 v0, v77, v0
	v_add_f32_e32 v0, v78, v0
	v_add_f32_e32 v0, v79, v0
	v_add_f32_e32 v0, v48, v0
	v_add_f32_e32 v0, v49, v0
	v_add_f32_e32 v0, v50, v0
	v_add_f32_e32 v0, v51, v0
	v_add_f32_e32 v0, v52, v0
	v_add_f32_e32 v0, v53, v0
	v_add_f32_e32 v0, v54, v0
	v_add_f32_e32 v0, v55, v0
	v_add_f32_e32 v0, v56, v0
	v_add_f32_e32 v0, v57, v0
	v_add_f32_e32 v0, v58, v0
	v_add_f32_e32 v0, v59, v0
	v_add_f32_e32 v0, v60, v0
	s_lshl_b64 s[16:17], s[10:11], 10
	v_add_f32_e32 v0, v61, v0
	s_cmp_lg_u32 0, -1
	v_add_f32_e32 v0, v62, v0
	s_cselect_b32 s10, 0, 0
	v_add_f32_e32 v0, v63, v0
	s_addk_i32 s10, 0x6000
	v_add_f32_e32 v0, v93, v0
	v_cvt_pk_bf16_f32 v48, v48, v49
	v_add3_u32 v95, v213, s10, v209
	v_cvt_pk_bf16_f32 v64, v64, v65
	v_cvt_pk_bf16_f32 v65, v66, v67
	v_cvt_pk_bf16_f32 v66, v68, v69
	v_cvt_pk_bf16_f32 v67, v70, v71
	v_cvt_pk_bf16_f32 v68, v72, v73
	v_cvt_pk_bf16_f32 v69, v74, v75
	v_cvt_pk_bf16_f32 v70, v76, v77
	v_cvt_pk_bf16_f32 v71, v78, v79
	v_cvt_pk_bf16_f32 v49, v50, v51
	v_cvt_pk_bf16_f32 v50, v52, v53
	v_cvt_pk_bf16_f32 v51, v54, v55
	v_cvt_pk_bf16_f32 v52, v56, v57
	v_cvt_pk_bf16_f32 v53, v58, v59
	v_cvt_pk_bf16_f32 v54, v60, v61
	v_cvt_pk_bf16_f32 v55, v62, v63
	v_add3_u32 v93, v95, v212, s87
	ds_read_b64_tr_b16 v[56:57],v93 offset:0
	ds_read_b64_tr_b16 v[58:59],v93 offset:512
	ds_read_b64_tr_b16 v[60:61],v93 offset:1024
	ds_read_b64_tr_b16 v[62:63],v93 offset:1536
	ds_read_b64_tr_b16 v[72:73],v93 offset:2048
	ds_read_b64_tr_b16 v[74:75],v93 offset:2560
	ds_read_b64_tr_b16 v[76:77],v93 offset:3072
	ds_read_b64_tr_b16 v[78:79],v93 offset:3584
	s_waitcnt lgkmcnt(0)
	s_nop 0
	v_mfma_f32_32x32x16_bf16 v[32:47], v[64:67], v[56:59], v[32:47]
	ds_read_b64_tr_b16 v[56:57],v93 offset:4096
	ds_read_b64_tr_b16 v[58:59],v93 offset:4608
	v_mfma_f32_32x32x16_bf16 v[32:47], v[68:71], v[60:63], v[32:47]
	ds_read_b64_tr_b16 v[60:61],v93 offset:5120
	ds_read_b64_tr_b16 v[62:63],v93 offset:5632
	v_mfma_f32_32x32x16_bf16 v[32:47], v[48:51], v[72:75], v[32:47]
	ds_read_b64_tr_b16 v[72:73],v93 offset:6144
	ds_read_b64_tr_b16 v[74:75],v93 offset:6656
	ds_read_b64_tr_b16 v[96:97],v93 offset:7168
	ds_read_b64_tr_b16 v[98:99],v93 offset:7680
	s_waitcnt lgkmcnt(0)
	v_mfma_f32_32x32x16_bf16 v[32:47], v[52:55], v[76:79], v[32:47]
	v_mfma_f32_32x32x16_bf16 v[16:31], v[64:67], v[56:59], v[16:31]
	v_cmp_gt_u32_e64 s[10:11], 32, v206
	v_mfma_f32_32x32x16_bf16 v[16:31], v[68:71], v[60:63], v[16:31]
	v_mfma_f32_32x32x16_bf16 v[16:31], v[48:51], v[72:75], v[16:31]
	v_mov_b32_e32 v48, v0
	s_nop 1
	v_permlane32_swap_b32_e32 v0, v48
	v_mfma_f32_32x32x16_bf16 v[16:31], v[52:55], v[96:99], v[16:31]
	s_and_saveexec_b64 s[60:61], s[10:11]
	v_add_f32_e32 v0, v0, v48
	ds_write_b32 v214, v0 offset:49280
	s_or_b64 exec, exec, s[60:61]
	s_waitcnt lgkmcnt(0)
	ds_read_b128 v[48:51], v94 offset:49280
	ds_read_b128 v[52:55], v94 offset:49312
	s_lshl_b64 s[16:17], s[16:17], 1
	s_add_u32 s16, s28, s16
	s_addc_u32 s17, s29, s17
	s_waitcnt lgkmcnt(1)
	v_rcp_f32_e32 v0, v48
	v_rcp_f32_e32 v56, v49
	s_add_u32 s12, s16, s12
	s_addc_u32 s13, s17, s13
	s_lshl_b32 s16, s78, 12
	s_add_i32 s16, s16, 0
	v_lshlrev_b32_e32 v63, 1, v207
	v_lshlrev_b32_e32 v64, 9, v208
	v_mul_f32_e32 v32, v32, v0
	v_mul_f32_e32 v0, v16, v0
	v_add3_u32 v63, s16, v63, v64
	v_cvt_pk_bf16_f32 v0, v0, s0
	v_rcp_f32_e32 v57, v50
	v_rcp_f32_e32 v58, v51
	s_waitcnt lgkmcnt(0)
	v_rcp_f32_e32 v59, v52
	ds_read_b128 v[48:51], v94 offset:49344
	v_rcp_f32_e32 v60, v53
	v_rcp_f32_e32 v61, v54
	v_rcp_f32_e32 v62, v55
	ds_read_b128 v[52:55], v94 offset:49376
	ds_write_b16 v63, v0 offset:51264
	v_mul_f32_e32 v0, v33, v56
	v_cvt_pk_bf16_f32 v0, v0, s0
	ds_write_b16 v63, v0 offset:51328
	v_mul_f32_e32 v0, v17, v56
	v_cvt_pk_bf16_f32 v0, v0, s0
	ds_write_b16 v63, v0 offset:51392
	v_mul_f32_e32 v0, v34, v57
	v_cvt_pk_bf16_f32 v0, v0, s0
	ds_write_b16 v63, v0 offset:51456
	v_mul_f32_e32 v0, v18, v57
	v_cvt_pk_bf16_f32 v0, v0, s0
	ds_write_b16 v63, v0 offset:51520
	v_mul_f32_e32 v0, v35, v58
	v_cvt_pk_bf16_f32 v0, v0, s0
	ds_write_b16 v63, v0 offset:51584
	v_mul_f32_e32 v0, v19, v58
	v_cvt_pk_bf16_f32 v0, v0, s0
	ds_write_b16 v63, v0 offset:51648
	v_mul_f32_e32 v0, v36, v59
	v_cvt_pk_bf16_f32 v0, v0, s0
	ds_write_b16 v63, v0 offset:52224
	v_mul_f32_e32 v0, v20, v59
	v_cvt_pk_bf16_f32 v0, v0, s0
	ds_write_b16 v63, v0 offset:52288
	v_mul_f32_e32 v0, v37, v60
	v_cvt_pk_bf16_f32 v0, v0, s0
	ds_write_b16 v63, v0 offset:52352
	v_mul_f32_e32 v0, v21, v60
	v_cvt_pk_bf16_f32 v0, v0, s0
	ds_write_b16 v63, v0 offset:52416
	v_mul_f32_e32 v0, v38, v61
	v_cvt_pk_bf16_f32 v0, v0, s0
	ds_write_b16 v63, v0 offset:52480
	v_mul_f32_e32 v0, v22, v61
	v_cvt_pk_bf16_f32 v0, v0, s0
	s_waitcnt lgkmcnt(13)
	v_rcp_f32_e32 v48, v48
	ds_write_b16 v63, v0 offset:52544
	v_mul_f32_e32 v0, v39, v62
	v_cvt_pk_bf16_f32 v0, v0, s0
	ds_write_b16 v63, v0 offset:52608
	v_mul_f32_e32 v0, v23, v62
	v_cvt_pk_bf16_f32 v0, v0, s0
	v_rcp_f32_e32 v49, v49
	ds_write_b16 v63, v0 offset:52672
	v_mul_f32_e32 v0, v40, v48
	v_cvt_pk_bf16_f32 v0, v0, s0
	ds_write_b16 v63, v0 offset:53248
	v_mul_f32_e32 v0, v24, v48
	v_cvt_pk_bf16_f32 v0, v0, s0
	v_rcp_f32_e32 v50, v50
	ds_write_b16 v63, v0 offset:53312
	v_mul_f32_e32 v0, v41, v49
	v_cvt_pk_bf16_f32 v0, v0, s0
	ds_write_b16 v63, v0 offset:53376
	v_mul_f32_e32 v0, v25, v49
	v_cvt_pk_bf16_f32 v0, v0, s0
	v_rcp_f32_e32 v51, v51
	ds_write_b16 v63, v0 offset:53440
	v_mul_f32_e32 v0, v42, v50
	v_cvt_pk_bf16_f32 v0, v0, s0
	ds_write_b16 v63, v0 offset:53504
	v_mul_f32_e32 v0, v26, v50
	v_cvt_pk_bf16_f32 v0, v0, s0
	s_waitcnt lgkmcnt(14)
	v_rcp_f32_e32 v52, v52
	ds_write_b16 v63, v0 offset:53568
	v_mul_f32_e32 v0, v43, v51
	v_cvt_pk_bf16_f32 v0, v0, s0
	ds_write_b16 v63, v0 offset:53632
	v_mul_f32_e32 v0, v27, v51
	v_cvt_pk_bf16_f32 v0, v0, s0
	v_rcp_f32_e32 v53, v53
	ds_write_b16 v63, v0 offset:53696
	v_mul_f32_e32 v0, v44, v52
	v_cvt_pk_bf16_f32 v0, v0, s0
	ds_write_b16 v63, v0 offset:54272
	v_mul_f32_e32 v0, v28, v52
	v_cvt_pk_bf16_f32 v0, v0, s0
	v_rcp_f32_e32 v54, v54
	ds_write_b16 v63, v0 offset:54336
	v_mul_f32_e32 v0, v45, v53
	v_cvt_pk_bf16_f32 v0, v0, s0
	ds_write_b16 v63, v0 offset:54400
	v_mul_f32_e32 v0, v29, v53
	v_cvt_pk_bf16_f32 v0, v0, s0
	v_rcp_f32_e32 v55, v55
	ds_write_b16 v63, v0 offset:54464
	v_mul_f32_e32 v0, v46, v54
	v_cvt_pk_bf16_f32 v0, v0, s0
	ds_write_b16 v63, v0 offset:54528
	v_mul_f32_e32 v0, v30, v54
	v_cvt_pk_bf16_f32 v0, v0, s0
	ds_write_b16 v63, v0 offset:54592
	v_mul_f32_e32 v0, v47, v55
	v_cvt_pk_bf16_f32 v0, v0, s0
	ds_write_b16 v63, v0 offset:54656
	v_mul_f32_e32 v0, v31, v55
	v_cvt_pk_bf16_f32 v32, v32, s0
	v_cvt_pk_bf16_f32 v0, v0, s0
	ds_write_b16 v63, v32 offset:51200
	ds_write_b16 v63, v0 offset:54720
	v_lshlrev_b32_e32 v0, 7, v14
	v_lshlrev_b32_e32 v14, 1, v90
	s_waitcnt lgkmcnt(0)
	v_add3_u32 v0, s16, v0, v14
	ds_read_b128 v[16:19], v0 offset:51200
	ds_read_b128 v[20:23], v0 offset:52224
	s_waitcnt vmcnt(3)
	v_lshlrev_b32_e32 v28, 16, v80
	v_and_b32_e32 v29, 0xffff0000, v80
	v_lshl_add_u64 v[24:25], v[88:89], 1, s[12:13]
	s_waitcnt lgkmcnt(1)
	v_lshlrev_b32_e32 v26, 16, v16
	v_and_b32_e32 v27, 0xffff0000, v16
	v_pk_mul_f32 v[26:27], v[28:29], v[26:27]
	v_lshlrev_b32_e32 v28, 16, v81
	v_cvt_pk_bf16_f32 v16, v26, v27
	v_lshlrev_b32_e32 v26, 16, v17
	v_and_b32_e32 v27, 0xffff0000, v17
	v_and_b32_e32 v29, 0xffff0000, v81
	v_pk_mul_f32 v[26:27], v[28:29], v[26:27]
	v_lshlrev_b32_e32 v28, 16, v82
	v_cvt_pk_bf16_f32 v17, v26, v27
	v_lshlrev_b32_e32 v26, 16, v18
	v_and_b32_e32 v27, 0xffff0000, v18
	v_and_b32_e32 v29, 0xffff0000, v82
	v_pk_mul_f32 v[26:27], v[28:29], v[26:27]
	v_lshlrev_b32_e32 v28, 16, v83
	v_cvt_pk_bf16_f32 v18, v26, v27
	v_lshlrev_b32_e32 v26, 16, v19
	v_and_b32_e32 v27, 0xffff0000, v19
	v_and_b32_e32 v29, 0xffff0000, v83
	v_pk_mul_f32 v[26:27], v[28:29], v[26:27]
	s_nop 0
	v_cvt_pk_bf16_f32 v19, v26, v27
	global_store_dwordx4 v[24:25], v[16:19], off sc1
	s_waitcnt lgkmcnt(0)
	s_nop 0
	v_lshlrev_b32_e32 v16, 16, v20
	v_and_b32_e32 v17, 0xffff0000, v20
	s_waitcnt vmcnt(3)
	v_lshlrev_b32_e32 v18, 16, v10
	v_and_b32_e32 v19, 0xffff0000, v10
	v_pk_mul_f32 v[16:17], v[18:19], v[16:17]
	v_lshlrev_b32_e32 v18, 16, v11
	v_cvt_pk_bf16_f32 v10, v16, v17
	v_lshlrev_b32_e32 v16, 16, v21
	v_and_b32_e32 v17, 0xffff0000, v21
	v_and_b32_e32 v19, 0xffff0000, v11
	v_pk_mul_f32 v[16:17], v[18:19], v[16:17]
	v_lshlrev_b32_e32 v18, 16, v12
	v_cvt_pk_bf16_f32 v11, v16, v17
	v_lshlrev_b32_e32 v16, 16, v22
	v_and_b32_e32 v17, 0xffff0000, v22
	v_and_b32_e32 v19, 0xffff0000, v12
	v_pk_mul_f32 v[16:17], v[18:19], v[16:17]
	v_lshlrev_b32_e32 v18, 16, v13
	v_cvt_pk_bf16_f32 v12, v16, v17
	v_lshlrev_b32_e32 v16, 16, v23
	v_and_b32_e32 v17, 0xffff0000, v23
	v_and_b32_e32 v19, 0xffff0000, v13
	v_pk_mul_f32 v[16:17], v[18:19], v[16:17]
	v_add_co_u32_e32 v20, vcc, s68, v24
	v_cvt_pk_bf16_f32 v13, v16, v17
	ds_read_b128 v[16:19], v0 offset:53248
	v_addc_co_u32_e32 v21, vcc, 0, v25, vcc
	global_store_dwordx4 v[20:21], v[10:13], off sc1
	ds_read_b128 v[10:13], v0 offset:54272
	s_waitcnt lgkmcnt(1)
	v_lshlrev_b32_e32 v20, 16, v16
	v_and_b32_e32 v21, 0xffff0000, v16
	s_waitcnt vmcnt(3)
	v_lshlrev_b32_e32 v22, 16, v6
	v_and_b32_e32 v23, 0xffff0000, v6
	v_pk_mul_f32 v[20:21], v[22:23], v[20:21]
	v_lshlrev_b32_e32 v16, 16, v17
	v_cvt_pk_bf16_f32 v6, v20, v21
	v_and_b32_e32 v17, 0xffff0000, v17
	v_lshlrev_b32_e32 v20, 16, v7
	v_and_b32_e32 v21, 0xffff0000, v7
	v_pk_mul_f32 v[16:17], v[20:21], v[16:17]
	v_lshlrev_b32_e32 v20, 16, v8
	v_cvt_pk_bf16_f32 v7, v16, v17
	v_lshlrev_b32_e32 v16, 16, v18
	v_and_b32_e32 v17, 0xffff0000, v18
	v_and_b32_e32 v21, 0xffff0000, v8
	v_pk_mul_f32 v[16:17], v[20:21], v[16:17]
	v_lshlrev_b32_e32 v18, 16, v9
	v_cvt_pk_bf16_f32 v8, v16, v17
	v_lshlrev_b32_e32 v16, 16, v19
	v_and_b32_e32 v17, 0xffff0000, v19
	v_and_b32_e32 v19, 0xffff0000, v9
	v_pk_mul_f32 v[16:17], v[18:19], v[16:17]
	s_nop 0
	v_cvt_pk_bf16_f32 v9, v16, v17
	v_add_co_u32_e32 v16, vcc, s70, v24
	s_nop 1
	v_addc_co_u32_e32 v17, vcc, 0, v25, vcc
	global_store_dwordx4 v[16:17], v[6:9], off sc1
	s_waitcnt lgkmcnt(0)
	s_nop 0
	v_lshlrev_b32_e32 v6, 16, v10
	v_and_b32_e32 v7, 0xffff0000, v10
	s_waitcnt vmcnt(3)
	v_lshlrev_b32_e32 v8, 16, v2
	v_and_b32_e32 v9, 0xffff0000, v2
	v_pk_mul_f32 v[6:7], v[8:9], v[6:7]
	v_lshlrev_b32_e32 v8, 16, v3
	v_cvt_pk_bf16_f32 v2, v6, v7
	v_lshlrev_b32_e32 v6, 16, v11
	v_and_b32_e32 v7, 0xffff0000, v11
	v_and_b32_e32 v9, 0xffff0000, v3
	v_pk_mul_f32 v[6:7], v[8:9], v[6:7]
	v_lshlrev_b32_e32 v8, 16, v4
	v_cvt_pk_bf16_f32 v3, v6, v7
	v_lshlrev_b32_e32 v6, 16, v12
	v_and_b32_e32 v7, 0xffff0000, v12
	v_and_b32_e32 v9, 0xffff0000, v4
	v_pk_mul_f32 v[6:7], v[8:9], v[6:7]
	v_lshlrev_b32_e32 v8, 16, v5
	v_cvt_pk_bf16_f32 v4, v6, v7
	v_lshlrev_b32_e32 v6, 16, v13
	v_and_b32_e32 v7, 0xffff0000, v13
	v_and_b32_e32 v9, 0xffff0000, v5
	v_pk_mul_f32 v[6:7], v[8:9], v[6:7]
	s_nop 0
	v_cvt_pk_bf16_f32 v5, v6, v7
	v_add_co_u32_e32 v6, vcc, 0xc000, v24
	s_nop 1
	v_addc_co_u32_e32 v7, vcc, 0, v25, vcc
	s_and_b64 vcc, exec, s[0:1]
	global_store_dwordx4 v[6:7], v[2:5], off sc1
	s_cbranch_vccnz .LBB0_544
	s_xor_b32 s20, s77, 1
	s_cmpk_gt_i32 s14, 0x3ff
	s_mov_b64 s[0:1], -1
	s_cbranch_scc1 .LBB0_661
	v_and_b32_e32 v7, 64, v205
	v_add_u32_e32 v3, -1, v205
	v_add_f32_e32 v0, v87, v15
	v_cmp_lt_i32_e32 vcc, v3, v7
	v_add_f32_e32 v2, v0, v92
	v_add_f32_e32 v6, v2, v91
	v_cndmask_b32_e32 v3, v3, v205, vcc
	v_lshlrev_b32_e32 v3, 2, v3
	ds_bpermute_b32 v3, v3, v6
	v_add_u32_e32 v4, -2, v205
	v_cmp_lt_i32_e32 vcc, v4, v7
	v_lshlrev_b32_e32 v5, 2, v206
	s_waitcnt lgkmcnt(0)
	v_add_f32_e32 v3, v6, v3
	v_cndmask_b32_e32 v4, v4, v205, vcc
	v_cndmask_b32_e64 v3, v3, v6, s[8:9]
	v_lshlrev_b32_e32 v4, 2, v4
	ds_bpermute_b32 v4, v4, v3
	v_cmp_gt_u32_e32 vcc, 2, v206
	s_waitcnt lgkmcnt(0)
	v_add_f32_e32 v4, v3, v4
	v_cndmask_b32_e32 v3, v4, v3, vcc
	v_add_u32_e32 v4, -4, v205
	v_cmp_lt_i32_e32 vcc, v4, v7
	s_nop 1
	v_cndmask_b32_e32 v4, v4, v205, vcc
	v_lshlrev_b32_e32 v4, 2, v4
	ds_bpermute_b32 v4, v4, v3
	v_cmp_gt_u32_e32 vcc, 4, v206
	s_waitcnt lgkmcnt(0)
	v_add_f32_e32 v4, v3, v4
	v_cndmask_b32_e32 v3, v4, v3, vcc
	v_add_u32_e32 v4, -8, v205
	v_cmp_lt_i32_e32 vcc, v4, v7
	s_nop 1
	v_cndmask_b32_e32 v4, v4, v205, vcc
	v_lshlrev_b32_e32 v4, 2, v4
	ds_bpermute_b32 v4, v4, v3
	v_cmp_gt_u32_e32 vcc, 8, v206
	s_waitcnt lgkmcnt(0)
	v_add_f32_e32 v4, v3, v4
	v_cndmask_b32_e32 v3, v4, v3, vcc
	v_add_u32_e32 v4, -16, v205
	v_cmp_lt_i32_e32 vcc, v4, v7
	s_nop 1
	v_cndmask_b32_e32 v4, v4, v205, vcc
	v_lshlrev_b32_e32 v4, 2, v4
	ds_bpermute_b32 v4, v4, v3
	v_cmp_gt_u32_e32 vcc, 16, v206
	s_waitcnt lgkmcnt(0)
	v_add_f32_e32 v4, v3, v4
	v_cndmask_b32_e32 v3, v4, v3, vcc
	v_subrev_u32_e32 v4, 32, v205
	v_cmp_lt_i32_e32 vcc, v4, v7
	v_add_u32_e32 v7, 64, v7
	s_nop 0
	v_cndmask_b32_e32 v4, v4, v205, vcc
	v_lshlrev_b32_e32 v4, 2, v4
	ds_bpermute_b32 v4, v4, v3
	s_waitcnt lgkmcnt(0)
	v_add_f32_e32 v4, v3, v4
	v_cndmask_b32_e64 v3, v4, v3, s[10:11]
	v_sub_f32_e32 v8, v3, v6
	v_xad_u32 v4, v5, -1, s15
	v_add_f32_e32 v5, v87, v8
	v_add_f32_e32 v3, v0, v8
	v_add_f32_e32 v0, v6, v8
	v_sub_f32_e32 v6, v5, v87
	v_cmp_ge_f32_e64 s[0:1], v6, -v197
	v_sub_f32_e32 v6, v3, v15
	v_add_f32_e32 v2, v2, v8
	v_cmp_lt_i32_e64 s[10:11], 0, v4
	v_cmp_ge_f32_e64 s[16:17], v6, -v197
	v_cmp_lt_i32_e64 s[12:13], -1, v4
	s_and_b64 s[16:17], s[10:11], s[16:17]
	v_sub_f32_e32 v8, v2, v92
	v_cndmask_b32_e64 v6, 0, 1, s[16:17]
	s_and_b64 vcc, s[12:13], s[0:1]
	v_cmp_lt_i32_e64 s[0:1], 1, v4
	v_cmp_ge_f32_e64 s[16:17], v8, -v197
	v_addc_co_u32_e32 v6, vcc, 0, v6, vcc
	s_and_b64 s[16:17], s[0:1], s[16:17]
	v_sub_f32_e32 v9, v0, v91
	v_cndmask_b32_e64 v8, 0, 1, s[16:17]
	v_cmp_lt_i32_e32 vcc, 2, v4
	v_cmp_ge_f32_e64 s[16:17], v9, -v197
	s_and_b64 s[16:17], vcc, s[16:17]
	s_nop 0
	v_addc_co_u32_e64 v6, s[16:17], v6, v8, s[16:17]
	v_xor_b32_e32 v8, 1, v205
	v_cmp_lt_i32_e64 s[16:17], v8, v7
	s_nop 1
	v_cndmask_b32_e64 v8, v205, v8, s[16:17]
	v_lshlrev_b32_e32 v8, 2, v8
	ds_bpermute_b32 v8, v8, v6
	s_waitcnt lgkmcnt(0)
	v_add_u32_e32 v6, v6, v8
	v_xor_b32_e32 v8, 2, v205
	v_cmp_lt_i32_e64 s[16:17], v8, v7
	s_nop 1
	v_cndmask_b32_e64 v8, v205, v8, s[16:17]
	v_lshlrev_b32_e32 v8, 2, v8
	ds_bpermute_b32 v8, v8, v6
	s_waitcnt lgkmcnt(0)
	v_add_u32_e32 v6, v6, v8
	v_xor_b32_e32 v8, 4, v205
	v_cmp_lt_i32_e64 s[16:17], v8, v7
	s_nop 1
	v_cndmask_b32_e64 v8, v205, v8, s[16:17]
	v_lshlrev_b32_e32 v8, 2, v8
	ds_bpermute_b32 v8, v8, v6
	s_waitcnt lgkmcnt(0)
	v_add_u32_e32 v6, v6, v8
	v_xor_b32_e32 v8, 8, v205
	v_cmp_lt_i32_e64 s[16:17], v8, v7
	s_nop 1
	v_cndmask_b32_e64 v8, v205, v8, s[16:17]
	v_lshlrev_b32_e32 v8, 2, v8
	ds_bpermute_b32 v8, v8, v6
	s_waitcnt lgkmcnt(0)
	v_add_u32_e32 v6, v6, v8
	v_xor_b32_e32 v8, 16, v205
	v_cmp_lt_i32_e64 s[16:17], v8, v7
	s_nop 1
	v_cndmask_b32_e64 v8, v205, v8, s[16:17]
	v_lshlrev_b32_e32 v8, 2, v8
	ds_bpermute_b32 v8, v8, v6
	s_waitcnt lgkmcnt(0)
	v_add_u32_e32 v6, v6, v8
	v_xor_b32_e32 v8, 32, v205
	v_cmp_lt_i32_e64 s[16:17], v8, v7
	s_nop 1
	v_cndmask_b32_e64 v7, v205, v8, s[16:17]
	v_lshlrev_b32_e32 v7, 2, v7
	ds_bpermute_b32 v7, v7, v6
	s_lshl_b32 s16, s20, 10
	s_add_i32 s56, s16, 0
	s_add_i32 s56, s56, 0x24800
	s_and_saveexec_b64 s[16:17], s[12:13]
	s_cbranch_execnz .LBB0_664
	s_or_b64 exec, exec, s[16:17]
	v_lshlrev_b32_e32 v4, 2, v4
	s_and_saveexec_b64 s[12:13], s[10:11]
	s_cbranch_execnz .LBB0_665

.LBB0_720:
	s_andn2_saveexec_b64 s[8:9], s[8:9]
	s_cbranch_execz .LBB0_740
	s_mov_b64 s[8:9], exec
	s_waitcnt lgkmcnt(0)
	s_waitcnt vmcnt(0)
	v_mbcnt_lo_u32_b32 v1, s8, 0
	v_mbcnt_hi_u32_b32 v1, s9, v1
	v_cmp_eq_u32_e32 vcc, 0, v1
	s_and_saveexec_b64 s[10:11], vcc
	s_cbranch_execz .LBB0_723
	s_bcnt1_i32_b64 s8, s[8:9]
	v_mov_b32_e32 v2, 0x3000
	v_mov_b32_e32 v3, s8
	global_atomic_add v2, v2, v3, s[52:53] offset:1024 sc0
